# adds: modulation-job rebalance, SSD scan one step ahead, gMLP conflict-free transposed image, SSD state update with reads in flight
# speedup vs baseline: 1.0468x; 1.0131x over previous
.LBB0_206:
	s_mov_b32 s76, 0x7f800000
	s_or_b64 exec, exec, s[30:31]
	s_ashr_i32 s34, s72, 4
	s_cmp_eq_u32 s54, 0
	s_cselect_b64 s[30:31], -1, 0
	s_cmp_lg_u32 s54, 0
	s_cselect_b64 s[54:55], -1, 0
	s_ashr_i32 s35, s34, 31
	s_lshl_b32 s37, s37, 2
	v_readlane_b32 s56, v254, 63
	s_add_u32 s37, s56, s37
	v_readlane_b32 s56, v255, 3
	s_addc_u32 s57, s56, 0
	s_add_u32 s56, s37, s44
	s_addc_u32 s57, s57, 0
	s_and_b64 s[58:59], s[30:31], exec
	s_mov_b32 s37, 0x392e0000
	s_cselect_b32 s37, 0x352e0000, s37
	v_readlane_b32 s44, v254, 61
	s_add_u32 s37, s44, s37
	v_readlane_b32 s44, v255, 1
	s_waitcnt vmcnt(2)
	v_mul_f32_e32 v32, 0x3fb8aa3b, v32
	s_addc_u32 s44, s44, 0
	s_lshl_b32 s36, s36, 7
	v_exp_f32_e32 v91, v32
	s_add_u32 s36, s37, s36
	v_cndmask_b32_e64 v32, v102, v95, s[30:31]
	s_addc_u32 s37, s44, 0
	v_mov_b32_e32 v89, v193
	s_mul_hi_i32 s74, s34, 0x900
	s_mul_i32 s75, s34, 0x900
	v_add_u32_e32 v201, 0x200, v33
	v_ashrrev_i32_e32 v33, 31, v32
	v_lshl_add_u64 v[34:35], s[36:37], 0, v[88:89]
	s_lshl_b64 s[34:35], s[34:35], 21
	v_lshlrev_b64 v[32:33], 10, v[32:33]
	v_lshl_add_u64 v[34:35], v[34:35], 0, s[34:35]
	v_mov_b32_e32 v40, 0
	s_mov_b32 s73, 0
	v_lshl_add_u64 v[92:93], v[34:35], 0, v[32:33]
	v_cndmask_b32_e64 v94, v149, v147, s[30:31]
	v_cndmask_b32_e64 v96, v150, v148, s[30:31]
	v_xor_b32_e32 v98, 0x80000000, v91
	v_mov_b32_e32 v41, v40
	v_mov_b32_e32 v42, v40
	v_mov_b32_e32 v43, v40
	v_mov_b32_e32 v32, v40
	v_mov_b32_e32 v33, v40
	v_mov_b32_e32 v34, v40
	v_mov_b32_e32 v35, v40
	v_mov_b32_e32 v36, v40
	v_mov_b32_e32 v37, v40
	v_mov_b32_e32 v38, v40
	v_mov_b32_e32 v39, v40
	v_mov_b32_e32 v44, v40
	v_mov_b32_e32 v45, v40
	v_mov_b32_e32 v46, v40
	v_mov_b32_e32 v47, v40
	s_and_b64 vcc, exec, s[0:1]
	s_cbranch_vccz .Lscan_ret0
	s_and_b64 s[98:99], s[30:31], exec
	s_cselect_b32 s98, 0, 0x80
	s_add_u32 s98, s75, s98
	s_addc_u32 s99, s74, 0
	s_mov_b32 s101, 0
	s_branch .Lscan_block

.Lscan_block:
	v_mov_b32_e32 v49, s99
	v_or_b32_e32 v48, s98, v94
	v_lshlrev_b64 v[48:49], 6, v[48:49]
	v_lshl_add_u64 v[48:49], s[56:57], 0, v[48:49]
	global_load_dword v48, v[48:49], off
	s_mov_b32 s34, 0x41a00000
	s_waitcnt vmcnt(0)
	v_add_f32_e32 v90, v199, v48
	v_cmp_nlt_f32_e32 vcc, s34, v90
	s_and_saveexec_b64 s[34:35], vcc
	s_cbranch_execz .Lscan_212
	v_mul_f32_e32 v48, 0x3fb8aa3b, v90
	v_exp_f32_e32 v62, v48
	s_mov_b32 s100, 0x3f2aaaab
	v_add_f32_e32 v50, 1.0, v62
	v_frexp_mant_f32_e32 v52, v50
	v_cvt_f64_f32_e32 v[48:49], v50
	v_frexp_exp_i32_f64_e32 v48, v[48:49]
	v_cmp_gt_f32_e32 vcc, s100, v52
	v_add_f32_e32 v51, -1.0, v50
	v_sub_f32_e32 v53, v51, v50
	v_subbrev_co_u32_e32 v56, vcc, 0, v48, vcc
	v_sub_u32_e32 v48, 0, v56
	v_sub_f32_e32 v51, v62, v51
	v_add_f32_e32 v53, 1.0, v53
	v_ldexp_f32 v49, v50, v48
	v_add_f32_e32 v51, v51, v53
	v_add_f32_e32 v50, -1.0, v49
	v_add_f32_e32 v52, 1.0, v49
	v_ldexp_f32 v48, v51, v48
	v_add_f32_e32 v51, 1.0, v50
	v_add_f32_e32 v53, -1.0, v52
	v_sub_f32_e32 v51, v49, v51
	v_sub_f32_e32 v49, v49, v53
	v_add_f32_e32 v51, v48, v51
	v_add_f32_e32 v48, v48, v49
	v_add_f32_e32 v57, v52, v48
	v_rcp_f32_e32 v59, v57
	v_sub_f32_e32 v49, v57, v52
	v_sub_f32_e32 v58, v48, v49
	v_add_f32_e32 v49, v50, v51
	v_mul_f32_e32 v61, v49, v59
	v_sub_f32_e32 v48, v49, v50
	v_mul_f32_e32 v50, v57, v61
	v_fma_f32 v52, v61, v57, -v50
	v_fmac_f32_e32 v52, v61, v58
	v_sub_f32_e32 v60, v51, v48
	v_add_f32_e32 v48, v50, v52
	v_sub_f32_e32 v51, v49, v48
	v_pk_add_f32 v[54:55], v[48:49], v[50:51] neg_lo:[0,1] neg_hi:[0,1]
	v_mov_b32_e32 v53, v48
	v_pk_add_f32 v[48:49], v[54:55], v[52:53] neg_lo:[0,1] neg_hi:[0,1]
	s_mov_b32 s100, 0x3f317218
	v_add_f32_e32 v49, v60, v49
	v_add_f32_e32 v48, v48, v49
	v_add_f32_e32 v49, v51, v48
	v_mul_f32_e32 v60, v59, v49
	v_mul_f32_e32 v50, v57, v60
	v_fma_f32 v52, v60, v57, -v50
	v_fmac_f32_e32 v52, v60, v58
	v_sub_f32_e32 v51, v51, v49
	v_add_f32_e32 v57, v48, v51
	v_add_f32_e32 v48, v50, v52
	v_sub_f32_e32 v51, v49, v48
	v_pk_add_f32 v[54:55], v[48:49], v[50:51] neg_lo:[0,1] neg_hi:[0,1]
	v_mov_b32_e32 v53, v48
	v_pk_add_f32 v[48:49], v[54:55], v[52:53] neg_lo:[0,1] neg_hi:[0,1]
	v_cmp_neq_f32_e32 vcc, s76, v62
	v_add_f32_e32 v49, v57, v49
	v_add_f32_e32 v48, v48, v49
	v_add_f32_e32 v49, v61, v60
	v_add_f32_e32 v48, v51, v48
	v_sub_f32_e32 v50, v49, v61
	v_mul_f32_e32 v48, v59, v48
	v_sub_f32_e32 v50, v60, v50
	v_add_f32_e32 v50, v50, v48
	v_add_f32_e32 v52, v49, v50
	v_mul_f32_e32 v53, v52, v52
	v_fmamk_f32 v48, v53, 0x3e9b6dac, v224
	v_fmaak_f32 v195, v53, v48, 0x3f2aaada
	v_cvt_f32_i32_e32 v48, v56
	v_sub_f32_e32 v49, v52, v49
	v_sub_f32_e32 v49, v50, v49
	v_ldexp_f32 v54, v49, 1
	v_mul_f32_e32 v49, v52, v53
	v_ldexp_f32 v51, v52, 1
	v_pk_mul_f32 v[52:53], v[48:49], v[194:195]
	s_nop 0
	v_fma_f32 v50, v48, s100, -v52
	v_fmac_f32_e32 v50, 0xb102e308, v48
	v_pk_add_f32 v[48:49], v[52:53], v[50:51]
	s_nop 0
	v_sub_f32_e32 v51, v49, v51
	v_sub_f32_e32 v51, v53, v51
	v_add_f32_e32 v55, v54, v51
	v_mov_b32_e32 v54, v52
	v_pk_add_f32 v[52:53], v[48:49], v[52:53] neg_lo:[0,1] neg_hi:[0,1]
	v_pk_add_f32 v[56:57], v[48:49], v[54:55]
	v_mov_b32_e32 v51, v48
	v_mov_b32_e32 v53, v57
	v_pk_add_f32 v[58:59], v[50:51], v[52:53] neg_lo:[0,1] neg_hi:[0,1]
	v_pk_add_f32 v[50:51], v[50:51], v[52:53]
	v_mov_b32_e32 v54, v55
	v_pk_add_f32 v[52:53], v[50:51], v[48:49] op_sel:[1,0] op_sel_hi:[0,1] neg_lo:[0,1] neg_hi:[0,1]
	v_pk_add_f32 v[60:61], v[56:57], v[52:53] op_sel_hi:[1,0] neg_lo:[0,1] neg_hi:[0,1]
	v_mov_b32_e32 v56, v57
	v_mov_b32_e32 v57, v51
	v_pk_mov_b32 v[52:53], v[48:49], v[52:53] op_sel:[1,0]
	v_mov_b32_e32 v55, v48
	v_pk_add_f32 v[52:53], v[56:57], v[52:53] neg_lo:[0,1] neg_hi:[0,1]
	v_mov_b32_e32 v60, v58
	v_pk_add_f32 v[48:49], v[54:55], v[52:53] neg_lo:[0,1] neg_hi:[0,1]
	v_mov_b32_e32 v59, v51
	v_pk_add_f32 v[52:53], v[60:61], v[48:49]
	s_nop 0
	v_pk_add_f32 v[54:55], v[52:53], v[52:53] op_sel:[0,1] op_sel_hi:[1,0]
	s_nop 0
	v_pk_add_f32 v[50:51], v[50:51], v[54:55] op_sel:[1,0] op_sel_hi:[0,1]
	v_mov_b32_e32 v53, v50
	v_pk_add_f32 v[56:57], v[52:53], v[58:59] neg_lo:[0,1] neg_hi:[0,1]
	v_mov_b32_e32 v49, v54
	v_sub_f32_e32 v51, v52, v56
	v_pk_add_f32 v[48:49], v[48:49], v[56:57] neg_lo:[0,1] neg_hi:[0,1]
	v_sub_f32_e32 v51, v58, v51
	v_add_f32_e32 v48, v48, v51
	v_add_f32_e32 v48, v48, v49
	v_add_f32_e32 v48, v50, v48
	v_cndmask_b32_e32 v48, v239, v48, vcc
	v_cmp_ngt_f32_e32 vcc, -1.0, v62
	s_nop 1
	v_cndmask_b32_e32 v48, v240, v48, vcc
	v_cmp_neq_f32_e32 vcc, -1.0, v62
	s_nop 1
	v_cndmask_b32_e32 v48, v241, v48, vcc
	v_cmp_lt_f32_e64 vcc, |v62|, s77
	s_nop 1
	v_cndmask_b32_e32 v90, v48, v62, vcc
.Lscan_212:
	s_or_b64 exec, exec, s[34:35]
	v_mov_b32_e32 v49, s99
	v_or_b32_e32 v48, s98, v96
	v_lshlrev_b64 v[48:49], 6, v[48:49]
	v_lshl_add_u64 v[48:49], s[56:57], 0, v[48:49]
	global_load_dword v48, v[48:49], off
	s_mov_b32 s34, 0x41a00000
	s_waitcnt vmcnt(0)
	v_add_f32_e32 v99, v199, v48
	v_cmp_nlt_f32_e32 vcc, s34, v99
	s_and_saveexec_b64 s[34:35], vcc
	s_cbranch_execz .Lscan_214
	v_mul_f32_e32 v48, 0x3fb8aa3b, v99
	v_exp_f32_e32 v62, v48
	s_mov_b32 s100, 0x3f2aaaab
	v_add_f32_e32 v50, 1.0, v62
	v_frexp_mant_f32_e32 v52, v50
	v_cvt_f64_f32_e32 v[48:49], v50
	v_frexp_exp_i32_f64_e32 v48, v[48:49]
	v_cmp_gt_f32_e32 vcc, s100, v52
	v_add_f32_e32 v51, -1.0, v50
	v_sub_f32_e32 v53, v51, v50
	v_subbrev_co_u32_e32 v56, vcc, 0, v48, vcc
	v_sub_u32_e32 v48, 0, v56
	v_sub_f32_e32 v51, v62, v51
	v_add_f32_e32 v53, 1.0, v53
	v_ldexp_f32 v49, v50, v48
	v_add_f32_e32 v51, v51, v53
	v_add_f32_e32 v50, -1.0, v49
	v_add_f32_e32 v52, 1.0, v49
	v_ldexp_f32 v48, v51, v48
	v_add_f32_e32 v51, 1.0, v50
	v_add_f32_e32 v53, -1.0, v52
	v_sub_f32_e32 v51, v49, v51
	v_sub_f32_e32 v49, v49, v53
	v_add_f32_e32 v51, v48, v51
	v_add_f32_e32 v48, v48, v49
	v_add_f32_e32 v57, v52, v48
	v_rcp_f32_e32 v59, v57
	v_sub_f32_e32 v49, v57, v52
	v_sub_f32_e32 v58, v48, v49
	v_add_f32_e32 v49, v50, v51
	v_mul_f32_e32 v61, v49, v59
	v_sub_f32_e32 v48, v49, v50
	v_mul_f32_e32 v50, v57, v61
	v_fma_f32 v52, v61, v57, -v50
	v_fmac_f32_e32 v52, v61, v58
	v_sub_f32_e32 v60, v51, v48
	v_add_f32_e32 v48, v50, v52
	v_sub_f32_e32 v51, v49, v48
	v_pk_add_f32 v[54:55], v[48:49], v[50:51] neg_lo:[0,1] neg_hi:[0,1]
	v_mov_b32_e32 v53, v48
	v_pk_add_f32 v[48:49], v[54:55], v[52:53] neg_lo:[0,1] neg_hi:[0,1]
	s_mov_b32 s100, 0x3f317218
	v_add_f32_e32 v49, v60, v49
	v_add_f32_e32 v48, v48, v49
	v_add_f32_e32 v49, v51, v48
	v_mul_f32_e32 v60, v59, v49
	v_mul_f32_e32 v50, v57, v60
	v_fma_f32 v52, v60, v57, -v50
	v_fmac_f32_e32 v52, v60, v58
	v_sub_f32_e32 v51, v51, v49
	v_add_f32_e32 v57, v48, v51
	v_add_f32_e32 v48, v50, v52
	v_sub_f32_e32 v51, v49, v48
	v_pk_add_f32 v[54:55], v[48:49], v[50:51] neg_lo:[0,1] neg_hi:[0,1]
	v_mov_b32_e32 v53, v48
	v_pk_add_f32 v[48:49], v[54:55], v[52:53] neg_lo:[0,1] neg_hi:[0,1]
	v_cmp_neq_f32_e32 vcc, s76, v62
	v_add_f32_e32 v49, v57, v49
	v_add_f32_e32 v48, v48, v49
	v_add_f32_e32 v49, v61, v60
	v_add_f32_e32 v48, v51, v48
	v_sub_f32_e32 v50, v49, v61
	v_mul_f32_e32 v48, v59, v48
	v_sub_f32_e32 v50, v60, v50
	v_add_f32_e32 v50, v50, v48
	v_add_f32_e32 v52, v49, v50
	v_mul_f32_e32 v53, v52, v52
	v_fmamk_f32 v48, v53, 0x3e9b6dac, v224
	v_fmaak_f32 v195, v53, v48, 0x3f2aaada
	v_cvt_f32_i32_e32 v48, v56
	v_sub_f32_e32 v49, v52, v49
	v_sub_f32_e32 v49, v50, v49
	v_ldexp_f32 v54, v49, 1
	v_mul_f32_e32 v49, v52, v53
	v_ldexp_f32 v51, v52, 1
	v_pk_mul_f32 v[52:53], v[48:49], v[194:195]
	s_nop 0
	v_fma_f32 v50, v48, s100, -v52
	v_fmac_f32_e32 v50, 0xb102e308, v48
	v_pk_add_f32 v[48:49], v[52:53], v[50:51]
	s_nop 0
	v_sub_f32_e32 v51, v49, v51
	v_sub_f32_e32 v51, v53, v51
	v_add_f32_e32 v55, v54, v51
	v_mov_b32_e32 v54, v52
	v_pk_add_f32 v[52:53], v[48:49], v[52:53] neg_lo:[0,1] neg_hi:[0,1]
	v_pk_add_f32 v[56:57], v[48:49], v[54:55]
	v_mov_b32_e32 v51, v48
	v_mov_b32_e32 v53, v57
	v_pk_add_f32 v[58:59], v[50:51], v[52:53] neg_lo:[0,1] neg_hi:[0,1]
	v_pk_add_f32 v[50:51], v[50:51], v[52:53]
	v_mov_b32_e32 v54, v55
	v_pk_add_f32 v[52:53], v[50:51], v[48:49] op_sel:[1,0] op_sel_hi:[0,1] neg_lo:[0,1] neg_hi:[0,1]
	v_pk_add_f32 v[60:61], v[56:57], v[52:53] op_sel_hi:[1,0] neg_lo:[0,1] neg_hi:[0,1]
	v_mov_b32_e32 v56, v57
	v_mov_b32_e32 v57, v51
	v_pk_mov_b32 v[52:53], v[48:49], v[52:53] op_sel:[1,0]
	v_mov_b32_e32 v55, v48
	v_pk_add_f32 v[52:53], v[56:57], v[52:53] neg_lo:[0,1] neg_hi:[0,1]
	v_mov_b32_e32 v60, v58
	v_pk_add_f32 v[48:49], v[54:55], v[52:53] neg_lo:[0,1] neg_hi:[0,1]
	v_mov_b32_e32 v59, v51
	v_pk_add_f32 v[52:53], v[60:61], v[48:49]
	s_nop 0
	v_pk_add_f32 v[54:55], v[52:53], v[52:53] op_sel:[0,1] op_sel_hi:[1,0]
	s_nop 0
	v_pk_add_f32 v[50:51], v[50:51], v[54:55] op_sel:[1,0] op_sel_hi:[0,1]
	v_mov_b32_e32 v53, v50
	v_pk_add_f32 v[56:57], v[52:53], v[58:59] neg_lo:[0,1] neg_hi:[0,1]
	v_mov_b32_e32 v49, v54
	v_sub_f32_e32 v51, v52, v56
	v_pk_add_f32 v[48:49], v[48:49], v[56:57] neg_lo:[0,1] neg_hi:[0,1]
	v_sub_f32_e32 v51, v58, v51
	v_add_f32_e32 v48, v48, v51
	v_add_f32_e32 v48, v48, v49
	v_add_f32_e32 v48, v50, v48
	v_cndmask_b32_e32 v48, v239, v48, vcc
	v_cmp_ngt_f32_e32 vcc, -1.0, v62
	s_nop 1
	v_cndmask_b32_e32 v48, v240, v48, vcc
	v_cmp_neq_f32_e32 vcc, -1.0, v62
	s_nop 1
	v_cndmask_b32_e32 v48, v241, v48, vcc
	v_cmp_lt_f32_e64 vcc, |v62|, s77
	s_nop 1
	v_cndmask_b32_e32 v99, v48, v62, vcc
.Lscan_214:
	s_or_b64 exec, exec, s[34:35]
	v_add_u32_e32 v50, -1, v229
	v_cmp_lt_i32_e32 vcc, v50, v230
	v_pk_mul_f32 v[48:49], v[90:91], v[98:99]
	v_add_u32_e32 v53, -4, v229
	v_cndmask_b32_e32 v50, v50, v229, vcc
	v_lshlrev_b32_e32 v52, 2, v50
	v_pk_fma_f32 v[50:51], v[90:91], v[98:99], v[48:49] op_sel:[0,0,1] op_sel_hi:[1,1,0] neg_lo:[0,0,1] neg_hi:[0,0,1]
	ds_bpermute_b32 v49, v52, v50
	v_add_u32_e32 v52, -2, v229
	v_cmp_lt_i32_e32 vcc, v52, v230
	s_waitcnt lgkmcnt(0)
	v_add_f32_e32 v49, v50, v49
	v_cndmask_b32_e32 v52, v52, v229, vcc
	v_lshlrev_b32_e32 v52, 2, v52
	v_cndmask_b32_e64 v49, v49, v50, s[18:19]
	ds_bpermute_b32 v52, v52, v49
	v_cmp_lt_i32_e32 vcc, v53, v230
	s_waitcnt lgkmcnt(0)
	v_add_f32_e32 v52, v49, v52
	v_cndmask_b32_e32 v53, v53, v229, vcc
	v_lshlrev_b32_e32 v53, 2, v53
	v_cndmask_b32_e64 v49, v52, v49, s[20:21]
	ds_bpermute_b32 v52, v53, v49
	v_add_u32_e32 v53, -8, v229
	v_cmp_lt_i32_e32 vcc, v53, v230
	s_waitcnt lgkmcnt(0)
	v_add_f32_e32 v52, v49, v52
	v_cndmask_b32_e32 v53, v53, v229, vcc
	v_lshlrev_b32_e32 v53, 2, v53
	v_cndmask_b32_e64 v49, v52, v49, s[22:23]
	ds_bpermute_b32 v52, v53, v49
	v_add_u32_e32 v53, -16, v229
	v_cmp_lt_i32_e32 vcc, v53, v230
	s_waitcnt lgkmcnt(0)
	v_add_f32_e32 v52, v49, v52
	v_cndmask_b32_e32 v53, v53, v229, vcc
	v_lshlrev_b32_e32 v53, 2, v53
	v_cndmask_b32_e64 v49, v52, v49, s[24:25]
	ds_bpermute_b32 v52, v53, v49
	v_subrev_u32_e32 v53, 32, v229
	v_cmp_lt_i32_e32 vcc, v53, v230
	s_waitcnt lgkmcnt(0)
	v_add_f32_e32 v52, v49, v52
	v_cndmask_b32_e32 v53, v53, v229, vcc
	v_lshlrev_b32_e32 v53, 2, v53
	v_cndmask_b32_e64 v49, v52, v49, s[26:27]
	ds_bpermute_b32 v52, v53, v49
	v_bfrev_b32_e32 v53, 0.5
	v_lshl_or_b32 v53, v229, 2, v53
	s_waitcnt lgkmcnt(0)
	v_add_f32_e32 v52, v49, v52
	v_cndmask_b32_e64 v49, v52, v49, s[28:29]
	ds_bpermute_b32 v53, v53, v49
	v_sub_f32_e32 v49, v49, v50
	v_pk_mov_b32 v[50:51], v[48:49], v[50:51] op_sel:[1,0]
	v_mov_b32_e32 v52, v90
	v_pk_add_f32 v[48:49], v[48:49], v[50:51]
	s_waitcnt lgkmcnt(0)
	v_sub_f32_e32 v50, v53, v48
	v_sub_f32_e32 v51, v53, v49
	v_mul_f32_e32 v50, 0x3fb8aa3b, v50
	v_mul_f32_e32 v51, 0x3fb8aa3b, v51
	v_exp_f32_e32 v50, v50
	v_exp_f32_e32 v51, v51
	v_mov_b32_e32 v53, v99
	v_mov_b32_e32 v210, v52
	v_mov_b32_e32 v211, v53
	v_mov_b32_e32 v212, v48
	v_mov_b32_e32 v213, v49
	v_pk_mul_f32 v[214:215], v[52:53], v[50:51]
	s_cmp_eq_u32 s101, 0
	s_cbranch_scc1 .Lscan_ret0
	s_branch .Lscan_ret1

.LBB0_208:
	v_readlane_b32 s34, v254, 7
	s_barrier
	s_nop 0
	v_mov_b32_e32 v65, s34
	ds_read_b32 v64, v65
	s_add_i32 s73, s73, 1
	s_cmp_eq_u32 s73, 18
	v_add_u32_e32 v236, v140, v103
	v_add_u32_e32 v237, v140, v105
	v_add_u32_e32 v242, v140, v106
	v_add_u32_e32 v243, v140, v107
	ds_read_b128 v[60:63], v236
	ds_read_b128 v[56:59], v237
	ds_read_b128 v[52:55], v242
	ds_read_b128 v[48:51], v243
	v_add_u32_e32 v236, v141, v103
	v_add_u32_e32 v237, v141, v105
	v_add_u32_e32 v242, v141, v106
	v_add_u32_e32 v243, v141, v107
	ds_read_b128 v[216:219], v236
	ds_read_b128 v[220:223], v237
	ds_read_b128 v[232:235], v242
	ds_read_b128 v[246:249], v243
	s_waitcnt lgkmcnt(8)
	v_mul_f32_e32 v64, 0x3fb8aa3b, v64
	v_exp_f32_e32 v64, v64
	s_nop 0
	v_pk_mul_f32 v[40:41], v[40:41], v[64:65] op_sel_hi:[1,0]
	v_pk_mul_f32 v[42:43], v[42:43], v[64:65] op_sel_hi:[1,0]
	v_pk_mul_f32 v[32:33], v[32:33], v[64:65] op_sel_hi:[1,0]
	v_pk_mul_f32 v[34:35], v[34:35], v[64:65] op_sel_hi:[1,0]
	v_pk_mul_f32 v[36:37], v[36:37], v[64:65] op_sel_hi:[1,0]
	v_pk_mul_f32 v[38:39], v[38:39], v[64:65] op_sel_hi:[1,0]
	v_pk_mul_f32 v[44:45], v[44:45], v[64:65] op_sel_hi:[1,0]
	v_pk_mul_f32 v[46:47], v[46:47], v[64:65] op_sel_hi:[1,0]
	s_waitcnt lgkmcnt(3)
	v_mfma_f32_16x16x32_bf16 v[40:43], v[216:219], v[60:63], v[40:43]
	v_add_u32_e32 v236, v142, v103
	ds_read_b128 v[216:219], v236
	s_waitcnt lgkmcnt(3)
	v_mfma_f32_16x16x32_bf16 v[40:43], v[220:223], v[56:59], v[40:43]
	v_add_u32_e32 v237, v142, v105
	ds_read_b128 v[220:223], v237
	s_waitcnt lgkmcnt(3)
	v_mfma_f32_16x16x32_bf16 v[40:43], v[232:235], v[52:55], v[40:43]
	v_add_u32_e32 v242, v142, v106
	ds_read_b128 v[232:235], v242
	s_waitcnt lgkmcnt(3)
	v_mfma_f32_16x16x32_bf16 v[40:43], v[246:249], v[48:51], v[40:43]
	v_add_u32_e32 v243, v142, v107
	ds_read_b128 v[246:249], v243
	s_nop 7
	v_cvt_pk_bf16_f32 v66, v40, v41
	v_cvt_pk_bf16_f32 v67, v42, v43
	ds_write_b64 v182, v[66:67]
	s_waitcnt lgkmcnt(4)
	v_mfma_f32_16x16x32_bf16 v[32:35], v[216:219], v[60:63], v[32:35]
	v_add_u32_e32 v236, v143, v103
	ds_read_b128 v[216:219], v236
	s_waitcnt lgkmcnt(4)
	v_mfma_f32_16x16x32_bf16 v[32:35], v[220:223], v[56:59], v[32:35]
	v_add_u32_e32 v237, v143, v105
	ds_read_b128 v[220:223], v237
	s_waitcnt lgkmcnt(4)
	v_mfma_f32_16x16x32_bf16 v[32:35], v[232:235], v[52:55], v[32:35]
	v_add_u32_e32 v242, v143, v106
	ds_read_b128 v[232:235], v242
	s_waitcnt lgkmcnt(4)
	v_mfma_f32_16x16x32_bf16 v[32:35], v[246:249], v[48:51], v[32:35]
	v_add_u32_e32 v243, v143, v107
	ds_read_b128 v[246:249], v243
	s_nop 7
	v_cvt_pk_bf16_f32 v66, v32, v33
	v_cvt_pk_bf16_f32 v67, v34, v35
	ds_write_b64 v183, v[66:67]
	s_waitcnt lgkmcnt(4)
	v_mfma_f32_16x16x32_bf16 v[36:39], v[216:219], v[60:63], v[36:39]
	v_add_u32_e32 v236, v104, v103
	ds_read_b128 v[216:219], v236
	s_waitcnt lgkmcnt(4)
	v_mfma_f32_16x16x32_bf16 v[36:39], v[220:223], v[56:59], v[36:39]
	v_add_u32_e32 v237, v104, v105
	ds_read_b128 v[220:223], v237
	s_waitcnt lgkmcnt(4)
	v_mfma_f32_16x16x32_bf16 v[36:39], v[232:235], v[52:55], v[36:39]
	v_add_u32_e32 v242, v104, v106
	ds_read_b128 v[232:235], v242
	s_waitcnt lgkmcnt(4)
	v_mfma_f32_16x16x32_bf16 v[36:39], v[246:249], v[48:51], v[36:39]
	v_add_u32_e32 v243, v104, v107
	ds_read_b128 v[246:249], v243
	s_nop 7
	v_cvt_pk_bf16_f32 v66, v36, v37
	v_cvt_pk_bf16_f32 v67, v38, v39
	ds_write_b64 v184, v[66:67]
	s_waitcnt lgkmcnt(4)
	v_mfma_f32_16x16x32_bf16 v[44:47], v[216:219], v[60:63], v[44:47]
	s_waitcnt lgkmcnt(3)
	v_mfma_f32_16x16x32_bf16 v[44:47], v[220:223], v[56:59], v[44:47]
	s_waitcnt lgkmcnt(2)
	v_mfma_f32_16x16x32_bf16 v[44:47], v[232:235], v[52:55], v[44:47]
	s_waitcnt lgkmcnt(1)
	v_mfma_f32_16x16x32_bf16 v[44:47], v[246:249], v[48:51], v[44:47]
	s_nop 7
	v_cvt_pk_bf16_f32 v66, v44, v45
	v_cvt_pk_bf16_f32 v67, v46, v47
	ds_write_b64 v185, v[66:67]
	s_cbranch_scc1 .LBB0_194
.LBB0_209:
	s_cmp_gt_u32 s73, 1
	s_cselect_b32 s34, 19, 1
	s_sub_i32 s36, s34, s73
	s_and_b64 s[34:35], s[30:31], exec
	s_cselect_b32 s44, s73, s36
	s_lshl_b32 s34, s44, 7
	s_ashr_i32 s35, s34, 31
	s_add_u32 s60, s75, s34
	s_addc_u32 s61, s74, s35
	s_andn2_b64 vcc, exec, s[0:1]
	s_waitcnt lgkmcnt(0)
	s_barrier
	s_cbranch_vccnz .LBB0_215
	ds_write_b64 v151, v[210:211]
	ds_write_b64 v152, v[212:213]
	ds_write_b64 v153, v[214:215]

.LBB0_223:
	s_waitcnt lgkmcnt(0)
	s_barrier
	s_and_b64 vcc, exec, s[0:1]
	s_cbranch_vccz .Lscan_ret1
	s_add_i32 s98, s73, 1
	s_cmp_gt_u32 s98, 17
	s_cbranch_scc1 .Lscan_ret1
	s_cmp_gt_u32 s98, 1
	s_cselect_b32 s99, 19, 1
	s_sub_i32 s99, s99, s98
	s_and_b64 s[100:101], s[30:31], exec
	s_cselect_b32 s98, s98, s99
	s_lshl_b32 s98, s98, 7
	s_add_u32 s98, s75, s98
	s_addc_u32 s99, s74, 0
	s_mov_b32 s101, 1
	s_branch .Lscan_block
.Lscan_ret1:
	s_and_saveexec_b64 s[64:65], s[36:37]
	s_cbranch_execz .LBB0_218
.LBB0_224:
	s_and_saveexec_b64 s[34:35], s[10:11]
	s_cbranch_execz .LBB0_226
	v_sub_u32_e32 v48, 0x7f, v68
	v_cndmask_b32_e64 v48, v48, v68, s[30:31]
	v_lshlrev_b32_e32 v49, 8, v48
	v_bitop3_b32 v48, v48, v146, 7 bitop3:0x6c
	v_lshlrev_b32_e32 v48, 4, v48
	v_add3_u32 v48, v144, v48, v49
	s_waitcnt vmcnt(7)
	ds_write_b128 v48, v[0:3]
	v_or_b32_e32 v48, 1, v68
	v_sub_u32_e32 v49, 0x7f, v48
	v_cndmask_b32_e64 v48, v49, v48, s[30:31]
	v_lshlrev_b32_e32 v49, 8, v48
	v_bitop3_b32 v48, v48, v146, 7 bitop3:0x6c
	v_lshlrev_b32_e32 v48, 4, v48
	v_add3_u32 v48, v144, v48, v49
	s_waitcnt vmcnt(6)
	ds_write_b128 v48, v[4:7]
	v_or_b32_e32 v48, 2, v68
	v_sub_u32_e32 v49, 0x7f, v48
	v_cndmask_b32_e64 v48, v49, v48, s[30:31]
	v_lshlrev_b32_e32 v49, 8, v48
	v_bitop3_b32 v48, v48, v146, 7 bitop3:0x6c
	v_lshlrev_b32_e32 v48, 4, v48
	v_add3_u32 v48, v144, v48, v49
	s_waitcnt vmcnt(5)
	ds_write_b128 v48, v[8:11]
	v_or_b32_e32 v48, 3, v68
	v_sub_u32_e32 v49, 0x7f, v48
	v_cndmask_b32_e64 v48, v49, v48, s[30:31]
	v_lshlrev_b32_e32 v49, 8, v48
	v_bitop3_b32 v48, v48, v146, 7 bitop3:0x6c
	v_lshlrev_b32_e32 v48, 4, v48
	v_add3_u32 v48, v144, v48, v49
	s_waitcnt vmcnt(4)
	ds_write_b128 v48, v[12:15]
	v_or_b32_e32 v48, 4, v68
	v_sub_u32_e32 v49, 0x7f, v48
	v_cndmask_b32_e64 v48, v49, v48, s[30:31]
	v_lshlrev_b32_e32 v49, 8, v48
	v_bitop3_b32 v48, v48, v146, 7 bitop3:0x6c
	v_lshlrev_b32_e32 v48, 4, v48
	v_add3_u32 v48, v144, v48, v49
	s_waitcnt vmcnt(3)
	ds_write_b128 v48, v[16:19]
	v_or_b32_e32 v48, 5, v68
	v_sub_u32_e32 v49, 0x7f, v48
	v_cndmask_b32_e64 v48, v49, v48, s[30:31]
	v_lshlrev_b32_e32 v49, 8, v48
	v_bitop3_b32 v48, v48, v146, 7 bitop3:0x6c
	v_lshlrev_b32_e32 v48, 4, v48
	v_add3_u32 v48, v144, v48, v49
	s_waitcnt vmcnt(2)
	ds_write_b128 v48, v[20:23]
	v_or_b32_e32 v48, 6, v68
	v_sub_u32_e32 v49, 0x7f, v48
	v_cndmask_b32_e64 v48, v49, v48, s[30:31]
	v_lshlrev_b32_e32 v49, 8, v48
	v_bitop3_b32 v48, v48, v146, 7 bitop3:0x6c
	v_lshlrev_b32_e32 v48, 4, v48
	v_add3_u32 v48, v144, v48, v49
	s_waitcnt vmcnt(1)
	ds_write_b128 v48, v[24:27]
	v_or_b32_e32 v48, 7, v68
	v_sub_u32_e32 v49, 0x7f, v48
	v_cndmask_b32_e64 v48, v49, v48, s[30:31]
	v_lshlrev_b32_e32 v49, 8, v48
	v_bitop3_b32 v48, v48, v146, 7 bitop3:0x6c
	v_lshlrev_b32_e32 v48, 4, v48
	v_add3_u32 v48, v144, v48, v49
	s_waitcnt vmcnt(0)
	ds_write_b128 v48, v[28:31]

.LBB0_332:
	s_or_b64 exec, exec, s[6:7]
	s_waitcnt lgkmcnt(0)
	s_lshl_b64 s[4:5], s[14:15], 11
	v_ashrrev_i32_e32 v64, 5, v177
	v_lshl_add_u32 v67, v64, 4, v179
	ds_read2_b32 v[70:71], v67 offset1:1
	ds_read2_b32 v[72:73], v67 offset0:2 offset1:3
	ds_read2_b32 v[74:75], v67 offset0:8 offset1:9
	ds_read2_b32 v[76:77], v67 offset0:10 offset1:11
	ds_read2_b32 v[78:79], v67 offset0:16 offset1:17
	ds_read2_b32 v[80:81], v67 offset0:18 offset1:19
	ds_read2_b32 v[82:83], v67 offset0:24 offset1:25
	ds_read2_b32 v[84:85], v67 offset0:26 offset1:27
	s_add_u32 s4, s10, s4
	s_addc_u32 s5, s11, s5
	s_add_u32 s4, s4, s18
	s_addc_u32 s5, s5, s19
	s_add_i32 s31, s31, 1
	v_readlane_b32 s6, v254, 41
	v_readlane_b32 s7, v254, 42
	v_and_b32_e32 v65, 31, v177
	v_lshlrev_b32_e32 v66, 8, v178
	v_lshl_add_u32 v66, v64, 10, v66
	v_lshl_add_u32 v66, v65, 1, v66
	v_add_u32_e32 v66, 0x11000, v66
	s_waitcnt lgkmcnt(0)
	v_rcp_f32_e32 v70, v70
	v_rcp_f32_e32 v71, v71
	v_rcp_f32_e32 v72, v72
	v_rcp_f32_e32 v73, v73
	v_rcp_f32_e32 v74, v74
	v_rcp_f32_e32 v75, v75
	v_rcp_f32_e32 v76, v76
	v_rcp_f32_e32 v77, v77
	v_rcp_f32_e32 v78, v78
	v_rcp_f32_e32 v79, v79
	v_rcp_f32_e32 v80, v80
	v_rcp_f32_e32 v81, v81
	v_rcp_f32_e32 v82, v82
	v_rcp_f32_e32 v83, v83
	v_rcp_f32_e32 v84, v84
	v_rcp_f32_e32 v85, v85
	s_nop 1
	v_mul_f32_e32 v0, v0, v70
	v_cvt_pk_bf16_f32 v0, v0, v193
	ds_write_b16 v66, v0 offset:0
	v_mul_f32_e32 v48, v48, v70
	v_cvt_pk_bf16_f32 v48, v48, v193
	ds_write_b16 v66, v48 offset:64
	v_mul_f32_e32 v32, v32, v70
	v_cvt_pk_bf16_f32 v32, v32, v193
	ds_write_b16 v66, v32 offset:128
	v_mul_f32_e32 v16, v16, v70
	v_cvt_pk_bf16_f32 v16, v16, v193
	ds_write_b16 v66, v16 offset:192
	v_mul_f32_e32 v1, v1, v71
	v_cvt_pk_bf16_f32 v1, v1, v193
	ds_write_b16 v66, v1 offset:256
	v_mul_f32_e32 v49, v49, v71
	v_cvt_pk_bf16_f32 v49, v49, v193
	ds_write_b16 v66, v49 offset:320
	v_mul_f32_e32 v33, v33, v71
	v_cvt_pk_bf16_f32 v33, v33, v193
	ds_write_b16 v66, v33 offset:384
	v_mul_f32_e32 v17, v17, v71
	v_cvt_pk_bf16_f32 v17, v17, v193
	ds_write_b16 v66, v17 offset:448
	s_waitcnt lgkmcnt(7)
	v_mul_f32_e32 v2, v2, v72
	v_cvt_pk_bf16_f32 v2, v2, v193
	ds_write_b16 v66, v2 offset:512
	v_mul_f32_e32 v50, v50, v72
	v_cvt_pk_bf16_f32 v50, v50, v193
	ds_write_b16 v66, v50 offset:576
	v_mul_f32_e32 v34, v34, v72
	v_cvt_pk_bf16_f32 v34, v34, v193
	ds_write_b16 v66, v34 offset:640
	v_mul_f32_e32 v18, v18, v72
	v_cvt_pk_bf16_f32 v18, v18, v193
	ds_write_b16 v66, v18 offset:704
	v_mul_f32_e32 v3, v3, v73
	v_cvt_pk_bf16_f32 v3, v3, v193
	ds_write_b16 v66, v3 offset:768
	v_mul_f32_e32 v51, v51, v73
	v_cvt_pk_bf16_f32 v51, v51, v193
	ds_write_b16 v66, v51 offset:832
	v_mul_f32_e32 v35, v35, v73
	v_cvt_pk_bf16_f32 v35, v35, v193
	ds_write_b16 v66, v35 offset:896
	v_mul_f32_e32 v19, v19, v73
	v_cvt_pk_bf16_f32 v19, v19, v193
	ds_write_b16 v66, v19 offset:960
	s_waitcnt lgkmcnt(7)
	v_mul_f32_e32 v4, v4, v74
	v_cvt_pk_bf16_f32 v4, v4, v193
	ds_write_b16 v66, v4 offset:2048
	v_mul_f32_e32 v52, v52, v74
	v_cvt_pk_bf16_f32 v52, v52, v193
	ds_write_b16 v66, v52 offset:2112
	v_mul_f32_e32 v36, v36, v74
	v_cvt_pk_bf16_f32 v36, v36, v193
	ds_write_b16 v66, v36 offset:2176
	v_mul_f32_e32 v20, v20, v74
	v_cvt_pk_bf16_f32 v20, v20, v193
	ds_write_b16 v66, v20 offset:2240
	v_mul_f32_e32 v5, v5, v75
	v_cvt_pk_bf16_f32 v5, v5, v193
	ds_write_b16 v66, v5 offset:2304
	v_mul_f32_e32 v53, v53, v75
	v_cvt_pk_bf16_f32 v53, v53, v193
	ds_write_b16 v66, v53 offset:2368
	v_mul_f32_e32 v37, v37, v75
	v_cvt_pk_bf16_f32 v37, v37, v193
	ds_write_b16 v66, v37 offset:2432
	v_mul_f32_e32 v21, v21, v75
	v_cvt_pk_bf16_f32 v21, v21, v193
	ds_write_b16 v66, v21 offset:2496
	s_waitcnt lgkmcnt(7)
	v_mul_f32_e32 v6, v6, v76
	v_cvt_pk_bf16_f32 v6, v6, v193
	ds_write_b16 v66, v6 offset:2560
	v_mul_f32_e32 v54, v54, v76
	v_cvt_pk_bf16_f32 v54, v54, v193
	ds_write_b16 v66, v54 offset:2624
	v_mul_f32_e32 v38, v38, v76
	v_cvt_pk_bf16_f32 v38, v38, v193
	ds_write_b16 v66, v38 offset:2688
	v_mul_f32_e32 v22, v22, v76
	v_cvt_pk_bf16_f32 v22, v22, v193
	ds_write_b16 v66, v22 offset:2752
	v_mul_f32_e32 v7, v7, v77
	v_cvt_pk_bf16_f32 v7, v7, v193
	ds_write_b16 v66, v7 offset:2816
	v_mul_f32_e32 v55, v55, v77
	v_cvt_pk_bf16_f32 v55, v55, v193
	ds_write_b16 v66, v55 offset:2880
	v_mul_f32_e32 v39, v39, v77
	v_cvt_pk_bf16_f32 v39, v39, v193
	ds_write_b16 v66, v39 offset:2944
	v_mul_f32_e32 v23, v23, v77
	v_cvt_pk_bf16_f32 v23, v23, v193
	ds_write_b16 v66, v23 offset:3008
	s_waitcnt lgkmcnt(7)
	v_mul_f32_e32 v8, v8, v78
	v_cvt_pk_bf16_f32 v8, v8, v193
	ds_write_b16 v66, v8 offset:4096
	v_mul_f32_e32 v56, v56, v78
	v_cvt_pk_bf16_f32 v56, v56, v193
	ds_write_b16 v66, v56 offset:4160
	v_mul_f32_e32 v40, v40, v78
	v_cvt_pk_bf16_f32 v40, v40, v193
	ds_write_b16 v66, v40 offset:4224
	v_mul_f32_e32 v24, v24, v78
	v_cvt_pk_bf16_f32 v24, v24, v193
	ds_write_b16 v66, v24 offset:4288
	v_mul_f32_e32 v9, v9, v79
	v_cvt_pk_bf16_f32 v9, v9, v193
	ds_write_b16 v66, v9 offset:4352
	v_mul_f32_e32 v57, v57, v79
	v_cvt_pk_bf16_f32 v57, v57, v193
	ds_write_b16 v66, v57 offset:4416
	v_mul_f32_e32 v41, v41, v79
	v_cvt_pk_bf16_f32 v41, v41, v193
	ds_write_b16 v66, v41 offset:4480
	v_mul_f32_e32 v25, v25, v79
	v_cvt_pk_bf16_f32 v25, v25, v193
	ds_write_b16 v66, v25 offset:4544
	s_waitcnt lgkmcnt(7)
	v_mul_f32_e32 v10, v10, v80
	v_cvt_pk_bf16_f32 v10, v10, v193
	ds_write_b16 v66, v10 offset:4608
	v_mul_f32_e32 v58, v58, v80
	v_cvt_pk_bf16_f32 v58, v58, v193
	ds_write_b16 v66, v58 offset:4672
	v_mul_f32_e32 v42, v42, v80
	v_cvt_pk_bf16_f32 v42, v42, v193
	ds_write_b16 v66, v42 offset:4736
	v_mul_f32_e32 v26, v26, v80
	v_cvt_pk_bf16_f32 v26, v26, v193
	ds_write_b16 v66, v26 offset:4800
	v_mul_f32_e32 v11, v11, v81
	v_cvt_pk_bf16_f32 v11, v11, v193
	ds_write_b16 v66, v11 offset:4864
	v_mul_f32_e32 v59, v59, v81
	v_cvt_pk_bf16_f32 v59, v59, v193
	ds_write_b16 v66, v59 offset:4928
	v_mul_f32_e32 v43, v43, v81
	v_cvt_pk_bf16_f32 v43, v43, v193
	ds_write_b16 v66, v43 offset:4992
	v_mul_f32_e32 v27, v27, v81
	v_cvt_pk_bf16_f32 v27, v27, v193
	ds_write_b16 v66, v27 offset:5056
	s_waitcnt lgkmcnt(7)
	v_mul_f32_e32 v12, v12, v82
	v_cvt_pk_bf16_f32 v12, v12, v193
	ds_write_b16 v66, v12 offset:6144
	v_mul_f32_e32 v60, v60, v82
	v_cvt_pk_bf16_f32 v60, v60, v193
	ds_write_b16 v66, v60 offset:6208
	v_mul_f32_e32 v44, v44, v82
	v_cvt_pk_bf16_f32 v44, v44, v193
	ds_write_b16 v66, v44 offset:6272
	v_mul_f32_e32 v28, v28, v82
	v_cvt_pk_bf16_f32 v28, v28, v193
	ds_write_b16 v66, v28 offset:6336
	v_mul_f32_e32 v13, v13, v83
	v_cvt_pk_bf16_f32 v13, v13, v193
	ds_write_b16 v66, v13 offset:6400
	v_mul_f32_e32 v61, v61, v83
	v_cvt_pk_bf16_f32 v61, v61, v193
	ds_write_b16 v66, v61 offset:6464
	v_mul_f32_e32 v45, v45, v83
	v_cvt_pk_bf16_f32 v45, v45, v193
	ds_write_b16 v66, v45 offset:6528
	v_mul_f32_e32 v29, v29, v83
	v_cvt_pk_bf16_f32 v29, v29, v193
	ds_write_b16 v66, v29 offset:6592
	s_waitcnt lgkmcnt(7)
	v_mul_f32_e32 v14, v14, v84
	v_cvt_pk_bf16_f32 v14, v14, v193
	ds_write_b16 v66, v14 offset:6656
	v_mul_f32_e32 v62, v62, v84
	v_cvt_pk_bf16_f32 v62, v62, v193
	ds_write_b16 v66, v62 offset:6720
	v_mul_f32_e32 v46, v46, v84
	v_cvt_pk_bf16_f32 v46, v46, v193
	ds_write_b16 v66, v46 offset:6784
	v_mul_f32_e32 v30, v30, v84
	v_cvt_pk_bf16_f32 v30, v30, v193
	ds_write_b16 v66, v30 offset:6848
	v_mul_f32_e32 v15, v15, v85
	v_cvt_pk_bf16_f32 v15, v15, v193
	ds_write_b16 v66, v15 offset:6912
	v_mul_f32_e32 v63, v63, v85
	v_cvt_pk_bf16_f32 v63, v63, v193
	ds_write_b16 v66, v63 offset:6976
	v_mul_f32_e32 v47, v47, v85
	v_cvt_pk_bf16_f32 v47, v47, v193
	ds_write_b16 v66, v47 offset:7040
	v_mul_f32_e32 v31, v31, v85
	v_cvt_pk_bf16_f32 v31, v31, v193
	ds_write_b16 v66, v31 offset:7104
	v_lshrrev_b32_e32 v64, 4, v177
	v_and_b32_e32 v65, 15, v177
	v_lshlrev_b32_e32 v66, 8, v178
	v_lshl_add_u32 v66, v64, 8, v66
	v_lshl_add_u32 v66, v65, 4, v66
	v_add_u32_e32 v66, 0x11000, v66
	v_add_u32_e32 v68, v178, v64
	v_mov_b32_e32 v69, 0
	v_lshlrev_b64 v[68:69], 11, v[68:69]
	v_lshl_add_u64 v[68:69], s[4:5], 0, v[68:69]
	v_lshlrev_b32_e32 v70, 4, v65
	v_mov_b32_e32 v71, 0
	v_lshl_add_u64 v[68:69], v[68:69], 0, v[70:71]
	s_waitcnt lgkmcnt(0)
	ds_read_b128 v[0:3], v66 offset:0
	ds_read_b128 v[4:7], v66 offset:1024
	ds_read_b128 v[8:11], v66 offset:2048
	ds_read_b128 v[12:15], v66 offset:3072
	ds_read_b128 v[16:19], v66 offset:4096
	ds_read_b128 v[20:23], v66 offset:5120
	ds_read_b128 v[24:27], v66 offset:6144
	ds_read_b128 v[28:31], v66 offset:7168
	s_waitcnt lgkmcnt(7)
	global_store_dwordx4 v[68:69], v[0:3], off offset:1024
	v_add_co_u32_e32 v68, vcc, 0x2000, v68
	s_nop 1
	v_addc_co_u32_e32 v69, vcc, 0, v69, vcc
	s_waitcnt lgkmcnt(6)
	global_store_dwordx4 v[68:69], v[4:7], off offset:1024
	v_add_co_u32_e32 v68, vcc, 0x2000, v68
	s_nop 1
	v_addc_co_u32_e32 v69, vcc, 0, v69, vcc
	s_waitcnt lgkmcnt(5)
	global_store_dwordx4 v[68:69], v[8:11], off offset:1024
	v_add_co_u32_e32 v68, vcc, 0x2000, v68
	s_nop 1
	v_addc_co_u32_e32 v69, vcc, 0, v69, vcc
	s_waitcnt lgkmcnt(4)
	global_store_dwordx4 v[68:69], v[12:15], off offset:1024
	v_add_co_u32_e32 v68, vcc, 0x2000, v68
	s_nop 1
	v_addc_co_u32_e32 v69, vcc, 0, v69, vcc
	s_waitcnt lgkmcnt(3)
	global_store_dwordx4 v[68:69], v[16:19], off offset:1024
	v_add_co_u32_e32 v68, vcc, 0x2000, v68
	s_nop 1
	v_addc_co_u32_e32 v69, vcc, 0, v69, vcc
	s_waitcnt lgkmcnt(2)
	global_store_dwordx4 v[68:69], v[20:23], off offset:1024
	v_add_co_u32_e32 v68, vcc, 0x2000, v68
	s_nop 1
	v_addc_co_u32_e32 v69, vcc, 0, v69, vcc
	s_waitcnt lgkmcnt(1)
	global_store_dwordx4 v[68:69], v[24:27], off offset:1024
	v_add_co_u32_e32 v68, vcc, 0x2000, v68
	s_nop 1
	v_addc_co_u32_e32 v69, vcc, 0, v69, vcc
	s_waitcnt lgkmcnt(0)
	global_store_dwordx4 v[68:69], v[28:31], off offset:1024
	s_branch .Lattn_epi_pad_end
	s_nop 0
	s_nop 0
	s_nop 0
	s_nop 0
	s_nop 0
	s_nop 0
	s_nop 0
	s_nop 0
	s_nop 0
	s_nop 0
	s_nop 0
	s_nop 0
	s_nop 0
	s_nop 0
	s_nop 0
	s_nop 0
	s_nop 0
	s_nop 0
	s_nop 0
	s_nop 0
	s_nop 0
	s_nop 0
	s_nop 0
	s_nop 0
	s_nop 0
	s_nop 0
	s_nop 0
	s_nop 0
	s_nop 0
	s_nop 0
	s_nop 0
	s_nop 0
	s_nop 0
	s_nop 0
	s_nop 0
	s_nop 0
	s_nop 0
	s_nop 0
	s_nop 0
	s_nop 0
	s_nop 0
	s_nop 0
	s_nop 0
	s_nop 0
	s_nop 0
	s_nop 0
	s_nop 0
	s_nop 0
	s_nop 0
	s_nop 0
	s_nop 0
	s_nop 0
	s_nop 0
	s_nop 0
	s_nop 0
	s_nop 0
	s_nop 0
	s_nop 0
	s_nop 0
	s_nop 0
	s_nop 0
	s_nop 0
	s_nop 0
	s_nop 0
	s_nop 0
	s_nop 0
	s_nop 0
	s_nop 0
	s_nop 0
	s_nop 0
	s_nop 0
	s_nop 0
	s_nop 0
	s_nop 0
	s_nop 0
.Lattn_epi_pad_end:
	s_mul_i32 s4, s31, s82
	s_add_i32 s14, s4, s6
	s_cmpk_lt_i32 s14, 0x480
	s_cbranch_scc0 .LBB0_358

.LBB0_358:
	v_readlane_b32 s4, v254, 41
	s_waitcnt vmcnt(63) expcnt(7) lgkmcnt(15)
	s_barrier
	s_cmpk_gt_i32 s4, 0x8ff
	v_readfirstlane_b32 s4, v176
	v_readlane_b32 s5, v254, 42
	s_cbranch_scc1 .LBB0_361
	s_add_u32 s12, s26, 0x3e80000
	s_addc_u32 s13, s27, 0
	s_lshl_b64 s[2:3], s[2:3], 3
	s_add_u32 s2, s70, s2
	v_and_b32_e32 v1, 15, v176
	s_addc_u32 s3, s71, s3
	s_ashr_i32 s4, s4, 6
	s_waitcnt vmcnt(5)
	v_lshlrev_b32_e32 v8, 8, v1
	v_lshlrev_b32_e32 v3, 4, v176
	v_lshl_or_b32 v0, s4, 12, v8
	v_and_b32_e32 v2, 48, v176
	v_and_b32_e32 v4, 0x70, v3
	s_waitcnt vmcnt(3)
	v_lshl_or_b32 v16, s4, 4, v1
	s_movk_i32 s4, 0x80
	v_bitop3_b32 v41, v2, v4, s4 bitop3:0x36
	s_movk_i32 s4, 0xc0
	v_bitop3_b32 v19, v3, v2, s33 bitop3:0x6c
	v_bitop3_b32 v35, v2, v4, 64 bitop3:0x36
	v_bitop3_b32 v43, v2, v4, s4 bitop3:0x36
	v_lshlrev_b32_e32 v2, 4, v1
	v_bitop3_b32 v64, v2, v176, s33 bitop3:0x78
	v_add_u32_e32 v2, 0x200, v176
	s_waitcnt vmcnt(1)
	v_ashrrev_i32_e32 v24, 4, v2
	v_lshrrev_b32_e32 v5, 2, v176
	s_waitcnt vmcnt(0)
	v_add_u32_e32 v29, 0, v0
	v_lshl_add_u32 v28, v24, 8, 0
	v_lshlrev_b32_e32 v4, 1, v24
	s_movk_i32 s6, 0xff02
	v_and_b32_e32 v18, 12, v5
	v_mad_u64_u32 v[2:3], s[4:5], v24, s6, v[28:29]
	v_xor_b32_e32 v5, 0x50, v4
	v_xad_u32 v3, v4, 16, 0
	v_xad_u32 v49, v4, 32, 0
	v_xad_u32 v50, v4, 48, 0
	v_xad_u32 v51, v4, 64, 0
	v_add_u32_e32 v52, 0, v5
	v_xor_b32_e32 v5, 0x60, v4
	v_xor_b32_e32 v4, 0x70, v4
	v_add_u32_e32 v54, 0, v4
	v_add_u32_e32 v4, 0x400, v176
	v_ashrrev_i32_e32 v30, 4, v4
	v_lshl_add_u32 v34, v30, 8, 0
	v_lshlrev_b32_e32 v6, 1, v30
	v_add_u32_e32 v53, 0, v5
	v_mad_u64_u32 v[4:5], s[4:5], v30, s6, v[34:35]
	v_xor_b32_e32 v7, 0x50, v6
	v_xad_u32 v5, v6, 16, 0
	v_xad_u32 v55, v6, 32, 0
	v_xad_u32 v56, v6, 48, 0
	v_xad_u32 v57, v6, 64, 0
	v_add_u32_e32 v58, 0, v7
	v_xor_b32_e32 v7, 0x60, v6
	v_xor_b32_e32 v6, 0x70, v6
	v_add_u32_e32 v60, 0, v6
	v_add_u32_e32 v6, 0x600, v176
	v_ashrrev_i32_e32 v36, 4, v6
	v_lshl_add_u32 v40, v36, 8, 0
	v_add_u32_e32 v59, 0, v7
	v_lshlrev_b32_e32 v61, 1, v36
	v_mad_u64_u32 v[6:7], s[4:5], v36, s6, v[40:41]
	s_load_dwordx2 s[6:7], s[2:3], 0x98
	v_ashrrev_i32_e32 v20, 4, v176
	v_xor_b32_e32 v67, 0x50, v61
	v_lshlrev_b32_e32 v0, 3, v1
	v_lshlrev_b32_e32 v65, 1, v20
	v_lshlrev_b32_e32 v1, 11, v1
	v_xad_u32 v7, v61, 16, 0
	v_xad_u32 v62, v61, 32, 0
	v_xad_u32 v63, v61, 48, 0
	v_xad_u32 v95, v61, 64, 0
	v_add_u32_e32 v96, 0, v67
	v_xor_b32_e32 v67, 0x60, v61
	v_xor_b32_e32 v61, 0x70, v61
	v_add_u32_e32 v9, 0, v19
	v_add_u32_e32 v10, 0, v35
	v_add_u32_e32 v11, 0, v41
	v_add_u32_e32 v12, 0, v43
	v_lshlrev_b32_e32 v22, 7, v20
	v_lshlrev_b32_e32 v13, 8, v20
	v_add_u32_e32 v14, 0, v64
	v_add_u32_e32 v66, 0, v1
	v_xor_b32_e32 v15, 16, v65
	v_xor_b32_e32 v42, 32, v65
	v_xor_b32_e32 v44, 48, v65
	v_xor_b32_e32 v45, 64, v65
	v_xor_b32_e32 v46, 0x50, v65
	v_xor_b32_e32 v47, 0x60, v65
	v_xor_b32_e32 v48, 0x70, v65
	v_lshlrev_b32_e32 v26, 7, v24
	v_lshlrev_b32_e32 v32, 7, v30
	v_lshlrev_b32_e32 v38, 7, v36
	v_add_u32_e32 v97, 0, v67
	v_add_u32_e32 v61, 0, v61
	v_readlane_b32 s2, v254, 41
	v_ashrrev_i32_e32 v17, 31, v16
	v_ashrrev_i32_e32 v23, 31, v22
	v_ashrrev_i32_e32 v21, 31, v20
	v_ashrrev_i32_e32 v27, 31, v26
	v_ashrrev_i32_e32 v25, 31, v24
	v_ashrrev_i32_e32 v33, 31, v32
	v_ashrrev_i32_e32 v31, 31, v30
	v_ashrrev_i32_e32 v39, 31, v38
	v_ashrrev_i32_e32 v37, 31, v36
	v_lshlrev_b32_e32 v192, 1, v0
	v_add_u32_e32 v67, v14, v13
	v_add_u32_e32 v68, v66, v15
	v_add_u32_e32 v69, v66, v42
	v_add_u32_e32 v70, v66, v44
	v_add_u32_e32 v71, v66, v45
	v_add_u32_e32 v72, v66, v46
	v_add_u32_e32 v73, v66, v47
	v_add_u32_e32 v74, v66, v48
	v_add_u32_e32 v75, v2, v1
	v_add_u32_e32 v76, v3, v1
	v_add_u32_e32 v77, v49, v1
	v_add_u32_e32 v78, v50, v1
	v_add_u32_e32 v79, v51, v1
	v_add_u32_e32 v80, v52, v1
	v_add_u32_e32 v81, v53, v1
	v_add_u32_e32 v82, v54, v1
	v_add_u32_e32 v83, v4, v1
	v_add_u32_e32 v84, v5, v1
	v_add_u32_e32 v85, v55, v1
	v_add_u32_e32 v86, v56, v1
	v_add_u32_e32 v87, v57, v1
	v_add_u32_e32 v88, v58, v1
	v_add_u32_e32 v89, v59, v1
	v_add_u32_e32 v90, v60, v1
	v_add_u32_e32 v91, v6, v1
	v_add_u32_e32 v92, v7, v1
	v_add_u32_e32 v93, v62, v1
	v_add_u32_e32 v94, v63, v1
	v_add_u32_e32 v95, v95, v1
	v_add_u32_e32 v96, v96, v1
	v_add_u32_e32 v97, v97, v1
	v_add_u32_e32 v98, v61, v1
	v_add_u32_e32 v99, v9, v8
	v_add_u32_e32 v100, v10, v8
	v_add_u32_e32 v101, v11, v8
	v_add_u32_e32 v102, v12, v8
	s_mov_b32 s14, s2
	s_mov_b32 s20, 0x3d372713
	s_mov_b32 s22, 0x3f4c422a
	v_readlane_b32 s3, v254, 42
	v_and_b32_e32 v154, 15, v176
	v_lshlrev_b32_e32 v154, 4, v154
	v_xor_b32_e32 v65, v154, v65
	v_xor_b32_e32 v68, v154, v68
	v_xor_b32_e32 v69, v154, v69
	v_xor_b32_e32 v70, v154, v70
	v_xor_b32_e32 v71, v154, v71
	v_xor_b32_e32 v72, v154, v72
	v_xor_b32_e32 v73, v154, v73
	v_xor_b32_e32 v74, v154, v74
	v_xor_b32_e32 v75, v154, v75
	v_xor_b32_e32 v76, v154, v76
	v_xor_b32_e32 v77, v154, v77
	v_xor_b32_e32 v78, v154, v78
	v_xor_b32_e32 v79, v154, v79
	v_xor_b32_e32 v80, v154, v80
	v_xor_b32_e32 v81, v154, v81
	v_xor_b32_e32 v82, v154, v82
	v_xor_b32_e32 v83, v154, v83
	v_xor_b32_e32 v84, v154, v84
	v_xor_b32_e32 v85, v154, v85
	v_xor_b32_e32 v86, v154, v86
	v_xor_b32_e32 v87, v154, v87
	v_xor_b32_e32 v88, v154, v88
	v_xor_b32_e32 v89, v154, v89
	v_xor_b32_e32 v90, v154, v90
	v_xor_b32_e32 v91, v154, v91
	v_xor_b32_e32 v92, v154, v92
	v_xor_b32_e32 v93, v154, v93
	v_xor_b32_e32 v94, v154, v94
	v_xor_b32_e32 v95, v154, v95
	v_xor_b32_e32 v96, v154, v96
	v_xor_b32_e32 v97, v154, v97
	v_xor_b32_e32 v98, v154, v98
	v_bfe_u32 v155, v176, 3, 1
	v_lshlrev_b32_e32 v155, 4, v155
	v_xor_b32_e32 v99, v155, v99
	v_xor_b32_e32 v100, v155, v100
	v_xor_b32_e32 v101, v155, v101
	v_xor_b32_e32 v102, v155, v102
	v_xor_b32_e32 v156, 0x20, v99
	v_xor_b32_e32 v157, 0x20, v100
	v_xor_b32_e32 v158, 0x20, v101
	v_xor_b32_e32 v159, 0x20, v102
	v_xor_b32_e32 v160, 0x40, v99
	v_xor_b32_e32 v161, 0x40, v100
	v_xor_b32_e32 v162, 0x40, v101
	v_xor_b32_e32 v163, 0x40, v102
	v_xor_b32_e32 v164, 0x60, v99
	v_xor_b32_e32 v165, 0x60, v100
	v_xor_b32_e32 v166, 0x60, v101
	v_xor_b32_e32 v167, 0x60, v102
	v_xor_b32_e32 v168, 0x80, v99
	v_xor_b32_e32 v169, 0x80, v100
	v_xor_b32_e32 v170, 0x80, v101
	v_xor_b32_e32 v171, 0x80, v102
	v_xor_b32_e32 v172, 0xa0, v99
	v_xor_b32_e32 v173, 0xa0, v100
	v_xor_b32_e32 v174, 0xa0, v101
	v_xor_b32_e32 v175, 0xa0, v102
	v_xor_b32_e32 v176, 0xc0, v99
	v_xor_b32_e32 v177, 0xc0, v100
	v_xor_b32_e32 v178, 0xc0, v101
	v_xor_b32_e32 v179, 0xc0, v102
	v_xor_b32_e32 v180, 0xe0, v99
	v_xor_b32_e32 v181, 0xe0, v100
	v_xor_b32_e32 v182, 0xe0, v101
	v_xor_b32_e32 v183, 0xe0, v102
	s_nop 0
	s_nop 0
	s_nop 0
	s_nop 0
	s_nop 0
	s_nop 0
	s_nop 0
.LBB0_360:
	s_ashr_i32 s2, s14, 2
	s_and_b32 s18, s14, 3
	s_ashr_i32 s3, s2, 31
	s_lshl_b64 s[2:3], s[2:3], 7
	s_lshl_b32 s4, s18, 15
	s_add_u32 s4, s12, s4
	s_addc_u32 s5, s13, 0
	v_lshl_add_u64 v[0:1], v[22:23], 1, s[4:5]
	v_lshl_add_u64 v[0:1], v[0:1], 0, v[192:193]
	s_waitcnt lgkmcnt(0)
	s_barrier
	global_load_dwordx4 v[120:123], v[0:1], off
	s_lshl_b32 s44, s18, 8
	v_add_u32_e32 v4, v66, v65
	s_lshl_b32 s15, s18, 7
	v_add_u32_e32 v44, s15, v16
	v_ashrrev_i32_e32 v45, 31, v44
	v_lshl_add_u64 v[44:45], v[44:45], 2, s[6:7]
	v_lshl_add_u64 v[56:57], s[2:3], 0, v[16:17]
	v_lshlrev_b32_e32 v46, 1, v18
	v_mov_b32_e32 v47, v193
	v_add_u32_e32 v8, v29, v41
	v_add_u32_e32 v12, v29, v43
	v_or_b32_e32 v103, s15, v18
	s_add_i32 s14, s14, s82
	s_cmpk_lt_i32 s14, 0x900
	v_lshl_add_u64 v[152:153], s[2:3], 0, v[20:21]
	v_lshlrev_b64 v[152:153], 12, v[152:153]
	v_lshl_add_u64 v[152:153], s[0:1], 0, v[152:153]
	v_lshl_add_u64 v[152:153], v[152:153], 0, s[44:45]
	v_lshl_add_u64 v[152:153], v[152:153], 0, v[192:193]
	global_load_dwordx4 v[124:127], v[152:153], off offset:1024
	v_lshl_add_u64 v[152:153], v[26:27], 1, s[4:5]
	v_lshl_add_u64 v[152:153], v[152:153], 0, v[192:193]
	global_load_dwordx4 v[128:131], v[152:153], off
	v_lshl_add_u64 v[152:153], s[2:3], 0, v[24:25]
	v_lshlrev_b64 v[152:153], 12, v[152:153]
	v_lshl_add_u64 v[152:153], s[0:1], 0, v[152:153]
	v_lshl_add_u64 v[152:153], v[152:153], 0, s[44:45]
	v_lshl_add_u64 v[152:153], v[152:153], 0, v[192:193]
	global_load_dwordx4 v[132:135], v[152:153], off offset:1024
	v_lshl_add_u64 v[152:153], v[32:33], 1, s[4:5]
	v_lshl_add_u64 v[152:153], v[152:153], 0, v[192:193]
	global_load_dwordx4 v[136:139], v[152:153], off
	v_lshl_add_u64 v[152:153], s[2:3], 0, v[30:31]
	v_lshlrev_b64 v[152:153], 12, v[152:153]
	v_lshl_add_u64 v[152:153], s[0:1], 0, v[152:153]
	v_lshl_add_u64 v[152:153], v[152:153], 0, s[44:45]
	v_lshl_add_u64 v[152:153], v[152:153], 0, v[192:193]
	global_load_dwordx4 v[140:143], v[152:153], off offset:1024
	v_lshl_add_u64 v[152:153], v[38:39], 1, s[4:5]
	v_lshl_add_u64 v[152:153], v[152:153], 0, v[192:193]
	global_load_dwordx4 v[144:147], v[152:153], off
	v_lshl_add_u64 v[152:153], s[2:3], 0, v[36:37]
	v_lshlrev_b64 v[152:153], 12, v[152:153]
	v_lshl_add_u64 v[152:153], s[0:1], 0, v[152:153]
	v_lshl_add_u64 v[152:153], v[152:153], 0, s[44:45]
	v_lshl_add_u64 v[152:153], v[152:153], 0, v[192:193]
	global_load_dwordx4 v[148:151], v[152:153], off offset:1024
	s_waitcnt vmcnt(7)
	ds_write_b128 v67, v[120:123]
	s_waitcnt vmcnt(6)
	ds_write_b16 v4, v124 offset:32768
	ds_write_b16_d16_hi v68, v124 offset:33024
	ds_write_b16 v69, v125 offset:33280
	ds_write_b16_d16_hi v70, v125 offset:33536
	ds_write_b16 v71, v126 offset:33792
	ds_write_b16_d16_hi v72, v126 offset:34048
	ds_write_b16 v73, v127 offset:34304
	ds_write_b16_d16_hi v74, v127 offset:34560
	v_add_u32_e32 v4, v28, v64
	s_waitcnt vmcnt(5)
	ds_write_b128 v4, v[128:131]
	s_waitcnt vmcnt(4)
	ds_write_b16 v75, v132 offset:32768
	ds_write_b16_d16_hi v76, v132 offset:33024
	ds_write_b16 v77, v133 offset:33280
	ds_write_b16_d16_hi v78, v133 offset:33536
	ds_write_b16 v79, v134 offset:33792
	ds_write_b16_d16_hi v80, v134 offset:34048
	ds_write_b16 v81, v135 offset:34304
	ds_write_b16_d16_hi v82, v135 offset:34560
	v_add_u32_e32 v4, v34, v64
	s_waitcnt vmcnt(3)
	ds_write_b128 v4, v[136:139]
	s_waitcnt vmcnt(2)
	ds_write_b16 v83, v140 offset:32768
	ds_write_b16_d16_hi v84, v140 offset:33024
	ds_write_b16 v85, v141 offset:33280
	ds_write_b16_d16_hi v86, v141 offset:33536
	ds_write_b16 v87, v142 offset:33792
	ds_write_b16_d16_hi v88, v142 offset:34048
	ds_write_b16 v89, v143 offset:34304
	ds_write_b16_d16_hi v90, v143 offset:34560
	v_add_u32_e32 v4, v40, v64
	s_waitcnt vmcnt(1)
	ds_write_b128 v4, v[144:147]
	s_waitcnt vmcnt(0)
	ds_write_b16 v91, v148 offset:32768
	ds_write_b16_d16_hi v92, v148 offset:33024
	ds_write_b16 v93, v149 offset:33280
	ds_write_b16_d16_hi v94, v149 offset:33536
	ds_write_b16 v95, v150 offset:33792
	ds_write_b16_d16_hi v96, v150 offset:34048
	ds_write_b16 v97, v151 offset:34304
	ds_write_b16_d16_hi v98, v151 offset:34560
	v_add_u32_e32 v4, v29, v35
	s_waitcnt lgkmcnt(0)
	s_barrier
	global_load_dword v42, v[44:45], off
	v_lshlrev_b64 v[44:45], 12, v[56:57]
	v_lshl_add_u64 v[44:45], s[0:1], 0, v[44:45]
	v_lshl_add_u64 v[44:45], v[44:45], 0, s[44:45]
	v_add_u32_e32 v0, v29, v19
	v_lshl_add_u64 v[44:45], v[44:45], 0, v[46:47]
	ds_read_b128 v[0:3], v0
	ds_read_b128 v[4:7], v4
	ds_read_b128 v[8:11], v8
	ds_read_b128 v[12:15], v12
	global_load_dwordx2 v[108:109], v[44:45], off
	global_load_dwordx2 v[58:59], v[44:45], off offset:32
	global_load_dwordx2 v[54:55], v[44:45], off offset:64
	global_load_dwordx2 v[52:53], v[44:45], off offset:96
	global_load_dwordx2 v[50:51], v[44:45], off offset:128
	global_load_dwordx2 v[48:49], v[44:45], off offset:160
	global_load_dwordx2 v[46:47], v[44:45], off offset:192
	s_nop 0
	global_load_dwordx2 v[44:45], v[44:45], off offset:224
	ds_read_b128 v[60:63], v99 offset:32768
	ds_read_b128 v[104:107], v100 offset:32768
	s_waitcnt lgkmcnt(1)
	v_mfma_f32_16x16x32_bf16 v[60:63], v[60:63], v[0:3], 0
	v_lshlrev_b64 v[56:57], 11, v[56:57]
	v_lshl_add_u64 v[56:57], s[10:11], 0, v[56:57]
	s_waitcnt lgkmcnt(0)
	v_mfma_f32_16x16x32_bf16 v[60:63], v[104:107], v[4:7], v[60:63]
	ds_read_b128 v[104:107], v101 offset:32768
	s_waitcnt lgkmcnt(0)
	v_mfma_f32_16x16x32_bf16 v[60:63], v[104:107], v[8:11], v[60:63]
	ds_read_b128 v[104:107], v102 offset:32768
	s_waitcnt lgkmcnt(0)
	v_mfma_f32_16x16x32_bf16 v[60:63], v[104:107], v[12:15], v[60:63]
	s_waitcnt vmcnt(7)
	v_lshlrev_b32_e32 v104, 16, v108
	v_and_b32_e32 v105, 0xffff0000, v108
	v_pk_mul_f32 v[106:107], v[104:105], s[20:21] op_sel_hi:[1,0]
	s_nop 3
	v_pk_add_f32 v[60:61], v[42:43], v[60:61] op_sel_hi:[0,1]
	v_pk_mul_f32 v[106:107], v[106:107], v[104:105]
	v_pk_add_f32 v[62:63], v[42:43], v[62:63] op_sel_hi:[0,1]
	v_pk_fma_f32 v[106:107], v[106:107], v[104:105], v[104:105]
	v_pk_mul_f32 v[104:105], v[104:105], 0.5 op_sel_hi:[1,0]
	v_pk_mul_f32 v[106:107], v[106:107], s[22:23] op_sel_hi:[1,0]
	s_nop 0
	v_mul_f32_e64 v108, |v106|, -2.0
	v_mul_f32_e32 v108, 0x3fb8aa3b, v108
	v_exp_f32_e32 v110, v108
	v_cmp_gt_f32_e32 vcc, 0, v106
	v_cmp_gt_f32_e64 s[4:5], 0, v107
	v_add_f32_e32 v108, 1.0, v110
	v_rcp_f32_e32 v112, v108
	v_mul_f32_e64 v108, |v107|, -2.0
	v_mul_f32_e32 v108, 0x3fb8aa3b, v108
	v_exp_f32_e32 v111, v108
	s_nop 0
	v_add_f32_e32 v108, 1.0, v111
	v_rcp_f32_e32 v113, v108
	v_pk_add_f32 v[114:115], v[110:111], 1.0 op_sel_hi:[1,0] neg_lo:[1,0] neg_hi:[1,0]
	s_nop 0
	v_pk_mul_f32 v[110:111], v[114:115], v[112:113]
	s_nop 0
	v_cndmask_b32_e64 v107, v111, -v111, s[4:5]
	v_cndmask_b32_e64 v106, v110, -v110, vcc
	v_pk_add_f32 v[106:107], v[106:107], 1.0 op_sel_hi:[1,0]
	s_nop 0
	v_pk_mul_f32 v[104:105], v[104:105], v[106:107]
	s_nop 0
	v_pk_mul_f32 v[60:61], v[60:61], v[104:105]
	v_lshlrev_b32_e32 v104, 16, v109
	v_and_b32_e32 v105, 0xffff0000, v109
	v_pk_mul_f32 v[106:107], v[104:105], s[20:21] op_sel_hi:[1,0]
	v_cvt_pk_bf16_f32 v60, v60, v61
	v_pk_mul_f32 v[106:107], v[106:107], v[104:105]
	s_nop 0
	v_pk_fma_f32 v[106:107], v[106:107], v[104:105], v[104:105]
	v_pk_mul_f32 v[104:105], v[104:105], 0.5 op_sel_hi:[1,0]
	v_pk_mul_f32 v[106:107], v[106:107], s[22:23] op_sel_hi:[1,0]
	s_nop 0
	v_mul_f32_e64 v108, |v106|, -2.0
	v_mul_f32_e32 v108, 0x3fb8aa3b, v108
	v_exp_f32_e32 v108, v108
	v_cmp_gt_f32_e32 vcc, 0, v106
	v_cmp_gt_f32_e64 s[4:5], 0, v107
	v_add_f32_e32 v109, 1.0, v108
	v_rcp_f32_e32 v110, v109
	v_mul_f32_e64 v109, |v107|, -2.0
	v_mul_f32_e32 v109, 0x3fb8aa3b, v109
	v_exp_f32_e32 v109, v109
	s_nop 0
	v_pk_add_f32 v[112:113], v[108:109], 1.0 op_sel_hi:[1,0] neg_lo:[1,0] neg_hi:[1,0]
	v_add_f32_e32 v108, 1.0, v109
	v_rcp_f32_e32 v111, v108
	s_nop 0
	v_pk_mul_f32 v[108:109], v[112:113], v[110:111]
	s_nop 0
	v_cndmask_b32_e64 v107, v109, -v109, s[4:5]
	v_cndmask_b32_e64 v106, v108, -v108, vcc
	v_pk_add_f32 v[106:107], v[106:107], 1.0 op_sel_hi:[1,0]
	s_nop 0
	v_pk_mul_f32 v[104:105], v[104:105], v[106:107]
	s_nop 0
	v_pk_mul_f32 v[62:63], v[62:63], v[104:105]
	ds_read_b128 v[104:107], v157 offset:36864
	v_cvt_pk_bf16_f32 v61, v62, v63
	v_lshlrev_b32_e32 v62, 1, v103
	v_mov_b32_e32 v63, v193
	v_lshl_add_u64 v[56:57], v[56:57], 0, v[62:63]
	global_store_dwordx2 v[56:57], v[60:61], off
	ds_read_b128 v[60:63], v156 offset:36864
	s_waitcnt lgkmcnt(0)
	v_mfma_f32_16x16x32_bf16 v[60:63], v[60:63], v[0:3], 0
	v_mfma_f32_16x16x32_bf16 v[60:63], v[104:107], v[4:7], v[60:63]
	ds_read_b128 v[104:107], v158 offset:36864
	s_waitcnt lgkmcnt(0)
	v_mfma_f32_16x16x32_bf16 v[60:63], v[104:107], v[8:11], v[60:63]
	ds_read_b128 v[104:107], v159 offset:36864
	s_waitcnt lgkmcnt(0)
	v_mfma_f32_16x16x32_bf16 v[60:63], v[104:107], v[12:15], v[60:63]
	s_waitcnt vmcnt(7)
	v_lshlrev_b32_e32 v104, 16, v58
	v_and_b32_e32 v105, 0xffff0000, v58
	v_pk_mul_f32 v[106:107], v[104:105], s[20:21] op_sel_hi:[1,0]
	s_nop 3
	v_pk_add_f32 v[60:61], v[42:43], v[60:61] op_sel_hi:[0,1]
	v_pk_mul_f32 v[106:107], v[106:107], v[104:105]
	v_pk_add_f32 v[62:63], v[42:43], v[62:63] op_sel_hi:[0,1]
	v_pk_fma_f32 v[106:107], v[106:107], v[104:105], v[104:105]
	v_pk_mul_f32 v[104:105], v[104:105], 0.5 op_sel_hi:[1,0]
	v_pk_mul_f32 v[106:107], v[106:107], s[22:23] op_sel_hi:[1,0]
	s_nop 0
	v_mul_f32_e64 v58, |v106|, -2.0
	v_mul_f32_e32 v58, 0x3fb8aa3b, v58
	v_exp_f32_e32 v108, v58
	v_cmp_gt_f32_e32 vcc, 0, v106
	v_cmp_gt_f32_e64 s[4:5], 0, v107
	v_add_f32_e32 v58, 1.0, v108
	v_rcp_f32_e32 v110, v58
	v_mul_f32_e64 v58, |v107|, -2.0
	v_mul_f32_e32 v58, 0x3fb8aa3b, v58
	v_exp_f32_e32 v109, v58
	s_nop 0
	v_add_f32_e32 v58, 1.0, v109
	v_rcp_f32_e32 v111, v58
	v_pk_add_f32 v[112:113], v[108:109], 1.0 op_sel_hi:[1,0] neg_lo:[1,0] neg_hi:[1,0]
	v_lshlrev_b32_e32 v58, 16, v59
	v_and_b32_e32 v59, 0xffff0000, v59
	v_pk_mul_f32 v[108:109], v[112:113], v[110:111]
	s_nop 0
	v_cndmask_b32_e64 v107, v109, -v109, s[4:5]
	v_cndmask_b32_e64 v106, v108, -v108, vcc
	v_pk_add_f32 v[106:107], v[106:107], 1.0 op_sel_hi:[1,0]
	s_nop 0
	v_pk_mul_f32 v[104:105], v[104:105], v[106:107]
	s_nop 0
	v_pk_mul_f32 v[60:61], v[104:105], v[60:61]
	v_pk_mul_f32 v[104:105], v[58:59], s[20:21] op_sel_hi:[1,0]
	v_cvt_pk_bf16_f32 v60, v60, v61
	v_pk_mul_f32 v[104:105], v[104:105], v[58:59]
	s_nop 0
	v_pk_fma_f32 v[104:105], v[104:105], v[58:59], v[58:59]
	v_pk_mul_f32 v[58:59], v[58:59], 0.5 op_sel_hi:[1,0]
	v_pk_mul_f32 v[104:105], v[104:105], s[22:23] op_sel_hi:[1,0]
	s_nop 0
	v_mul_f32_e64 v103, |v104|, -2.0
	v_mul_f32_e32 v103, 0x3fb8aa3b, v103
	v_exp_f32_e32 v106, v103
	v_cmp_gt_f32_e32 vcc, 0, v104
	v_cmp_gt_f32_e64 s[4:5], 0, v105
	v_add_f32_e32 v103, 1.0, v106
	v_rcp_f32_e32 v108, v103
	v_mul_f32_e64 v103, |v105|, -2.0
	v_mul_f32_e32 v103, 0x3fb8aa3b, v103
	v_exp_f32_e32 v107, v103
	s_nop 0
	v_add_f32_e32 v103, 1.0, v107
	v_rcp_f32_e32 v109, v103
	v_pk_add_f32 v[110:111], v[106:107], 1.0 op_sel_hi:[1,0] neg_lo:[1,0] neg_hi:[1,0]
	s_nop 0
	v_pk_mul_f32 v[106:107], v[110:111], v[108:109]
	s_nop 0
	v_cndmask_b32_e64 v105, v107, -v107, s[4:5]
	v_cndmask_b32_e64 v104, v106, -v106, vcc
	v_pk_add_f32 v[104:105], v[104:105], 1.0 op_sel_hi:[1,0]
	s_nop 0
	v_pk_mul_f32 v[58:59], v[58:59], v[104:105]
	ds_read_b128 v[104:107], v161 offset:40960
	v_pk_mul_f32 v[58:59], v[58:59], v[62:63]
	s_waitcnt vmcnt(6)
	v_lshlrev_b32_e32 v62, 16, v54
	v_cvt_pk_bf16_f32 v61, v58, v59
	global_store_dwordx2 v[56:57], v[60:61], off offset:32
	ds_read_b128 v[58:61], v160 offset:40960
	s_waitcnt lgkmcnt(0)
	v_mfma_f32_16x16x32_bf16 v[58:61], v[58:61], v[0:3], 0
	v_and_b32_e32 v63, 0xffff0000, v54
	v_mfma_f32_16x16x32_bf16 v[58:61], v[104:107], v[4:7], v[58:61]
	ds_read_b128 v[104:107], v162 offset:40960
	s_waitcnt lgkmcnt(0)
	v_mfma_f32_16x16x32_bf16 v[58:61], v[104:107], v[8:11], v[58:61]
	ds_read_b128 v[104:107], v163 offset:40960
	s_waitcnt lgkmcnt(0)
	v_mfma_f32_16x16x32_bf16 v[58:61], v[104:107], v[12:15], v[58:61]
	v_mul_f32_e64 v104, v62, s20
	v_mul_f32_e64 v105, v63, s20
	s_nop 5
	v_pk_add_f32 v[58:59], v[42:43], v[58:59] op_sel_hi:[0,1]
	v_pk_mul_f32 v[104:105], v[104:105], v[62:63]
	v_pk_add_f32 v[60:61], v[42:43], v[60:61] op_sel_hi:[0,1]
	v_pk_fma_f32 v[104:105], v[104:105], v[62:63], v[62:63]
	v_pk_mul_f32 v[62:63], v[62:63], 0.5 op_sel_hi:[1,0]
	v_pk_mul_f32 v[104:105], v[104:105], s[22:23] op_sel_hi:[1,0]
	s_nop 0
	v_mul_f32_e64 v54, |v104|, -2.0
	v_mul_f32_e32 v54, 0x3fb8aa3b, v54
	v_exp_f32_e32 v106, v54
	v_cmp_gt_f32_e32 vcc, 0, v104
	v_cmp_gt_f32_e64 s[4:5], 0, v105
	v_add_f32_e32 v54, 1.0, v106
	v_rcp_f32_e32 v108, v54
	v_mul_f32_e64 v54, |v105|, -2.0
	v_mul_f32_e32 v54, 0x3fb8aa3b, v54
	v_exp_f32_e32 v107, v54
	s_nop 0
	v_add_f32_e32 v54, 1.0, v107
	v_rcp_f32_e32 v109, v54
	v_pk_add_f32 v[110:111], v[106:107], 1.0 op_sel_hi:[1,0] neg_lo:[1,0] neg_hi:[1,0]
	v_lshlrev_b32_e32 v54, 16, v55
	v_and_b32_e32 v55, 0xffff0000, v55
	v_pk_mul_f32 v[106:107], v[110:111], v[108:109]
	s_nop 0
	v_cndmask_b32_e64 v105, v107, -v107, s[4:5]
	v_cndmask_b32_e64 v104, v106, -v106, vcc
	v_pk_add_f32 v[104:105], v[104:105], 1.0 op_sel_hi:[1,0]
	s_nop 0
	v_pk_mul_f32 v[62:63], v[62:63], v[104:105]
	s_nop 0
	v_pk_mul_f32 v[58:59], v[62:63], v[58:59]
	v_pk_mul_f32 v[62:63], v[54:55], s[20:21] op_sel_hi:[1,0]
	v_cvt_pk_bf16_f32 v58, v58, v59
	v_pk_mul_f32 v[62:63], v[62:63], v[54:55]
	s_nop 0
	v_pk_fma_f32 v[62:63], v[62:63], v[54:55], v[54:55]
	v_pk_mul_f32 v[54:55], v[54:55], 0.5 op_sel_hi:[1,0]
	v_pk_mul_f32 v[62:63], v[62:63], s[22:23] op_sel_hi:[1,0]
	s_nop 0
	v_mul_f32_e64 v103, |v62|, -2.0
	v_mul_f32_e32 v103, 0x3fb8aa3b, v103
	v_exp_f32_e32 v104, v103
	v_cmp_gt_f32_e32 vcc, 0, v62
	v_cmp_gt_f32_e64 s[4:5], 0, v63
	v_add_f32_e32 v103, 1.0, v104
	v_rcp_f32_e32 v106, v103
	v_mul_f32_e64 v103, |v63|, -2.0
	v_mul_f32_e32 v103, 0x3fb8aa3b, v103
	v_exp_f32_e32 v105, v103
	s_nop 0
	v_add_f32_e32 v103, 1.0, v105
	v_rcp_f32_e32 v107, v103
	v_pk_add_f32 v[108:109], v[104:105], 1.0 op_sel_hi:[1,0] neg_lo:[1,0] neg_hi:[1,0]
	s_nop 0
	v_pk_mul_f32 v[104:105], v[108:109], v[106:107]
	s_nop 0
	v_cndmask_b32_e64 v63, v105, -v105, s[4:5]
	v_cndmask_b32_e64 v62, v104, -v104, vcc
	v_pk_add_f32 v[62:63], v[62:63], 1.0 op_sel_hi:[1,0]
	ds_read_b128 v[104:107], v165 offset:45056
	v_pk_mul_f32 v[54:55], v[54:55], v[62:63]
	s_nop 0
	v_pk_mul_f32 v[54:55], v[54:55], v[60:61]
	s_nop 0
	v_cvt_pk_bf16_f32 v59, v54, v55
	global_store_dwordx2 v[56:57], v[58:59], off offset:64
	ds_read_b128 v[58:61], v164 offset:45056
	s_waitcnt lgkmcnt(0)
	v_mfma_f32_16x16x32_bf16 v[58:61], v[58:61], v[0:3], 0
	s_waitcnt vmcnt(7)
	v_lshlrev_b32_e32 v54, 16, v52
	v_and_b32_e32 v55, 0xffff0000, v52
	v_pk_mul_f32 v[62:63], v[54:55], s[20:21] op_sel_hi:[1,0]
	v_mfma_f32_16x16x32_bf16 v[58:61], v[104:107], v[4:7], v[58:61]
	ds_read_b128 v[104:107], v166 offset:45056
	v_pk_mul_f32 v[62:63], v[62:63], v[54:55]
	s_waitcnt lgkmcnt(0)
	v_mfma_f32_16x16x32_bf16 v[58:61], v[104:107], v[8:11], v[58:61]
	ds_read_b128 v[104:107], v167 offset:45056
	v_pk_fma_f32 v[62:63], v[62:63], v[54:55], v[54:55]
	v_pk_mul_f32 v[54:55], v[54:55], 0.5 op_sel_hi:[1,0]
	v_pk_mul_f32 v[62:63], v[62:63], s[22:23] op_sel_hi:[1,0]
	s_waitcnt lgkmcnt(0)
	v_mfma_f32_16x16x32_bf16 v[58:61], v[104:107], v[12:15], v[58:61]
	v_mul_f32_e64 v52, |v62|, -2.0
	v_mul_f32_e32 v52, 0x3fb8aa3b, v52
	v_exp_f32_e32 v104, v52
	v_cmp_gt_f32_e32 vcc, 0, v62
	v_cmp_gt_f32_e64 s[4:5], 0, v63
	s_nop 2
	v_pk_add_f32 v[58:59], v[42:43], v[58:59] op_sel_hi:[0,1]
	v_add_f32_e32 v52, 1.0, v104
	v_rcp_f32_e32 v106, v52
	v_mul_f32_e64 v52, |v63|, -2.0
	v_mul_f32_e32 v52, 0x3fb8aa3b, v52
	v_exp_f32_e32 v105, v52
	s_nop 0
	v_add_f32_e32 v52, 1.0, v105
	v_rcp_f32_e32 v107, v52
	v_pk_add_f32 v[108:109], v[104:105], 1.0 op_sel_hi:[1,0] neg_lo:[1,0] neg_hi:[1,0]
	v_lshlrev_b32_e32 v52, 16, v53
	v_and_b32_e32 v53, 0xffff0000, v53
	v_pk_mul_f32 v[104:105], v[108:109], v[106:107]
	s_nop 0
	v_cndmask_b32_e64 v63, v105, -v105, s[4:5]
	v_cndmask_b32_e64 v62, v104, -v104, vcc
	v_pk_add_f32 v[62:63], v[62:63], 1.0 op_sel_hi:[1,0]
	s_nop 0
	v_pk_mul_f32 v[54:55], v[54:55], v[62:63]
	s_nop 0
	v_pk_mul_f32 v[54:55], v[54:55], v[58:59]
	v_pk_mul_f32 v[58:59], v[52:53], s[20:21] op_sel_hi:[1,0]
	v_cvt_pk_bf16_f32 v54, v54, v55
	v_pk_mul_f32 v[58:59], v[58:59], v[52:53]
	s_nop 0
	v_pk_fma_f32 v[58:59], v[58:59], v[52:53], v[52:53]
	v_pk_mul_f32 v[52:53], v[52:53], 0.5 op_sel_hi:[1,0]
	v_pk_mul_f32 v[58:59], v[58:59], s[22:23] op_sel_hi:[1,0]
	s_nop 0
	v_mul_f32_e64 v62, |v58|, -2.0
	v_mul_f32_e32 v62, 0x3fb8aa3b, v62
	v_exp_f32_e32 v62, v62
	v_cmp_gt_f32_e32 vcc, 0, v58
	v_cmp_gt_f32_e64 s[4:5], 0, v59
	v_add_f32_e32 v63, 1.0, v62
	v_rcp_f32_e32 v104, v63
	v_mul_f32_e64 v63, |v59|, -2.0
	v_mul_f32_e32 v63, 0x3fb8aa3b, v63
	v_exp_f32_e32 v63, v63
	s_nop 0
	v_pk_add_f32 v[106:107], v[62:63], 1.0 op_sel_hi:[1,0] neg_lo:[1,0] neg_hi:[1,0]
	v_add_f32_e32 v62, 1.0, v63
	v_rcp_f32_e32 v105, v62
	s_nop 0
	v_pk_mul_f32 v[62:63], v[106:107], v[104:105]
	s_nop 0
	v_cndmask_b32_e64 v59, v63, -v63, s[4:5]
	v_cndmask_b32_e64 v58, v62, -v62, vcc
	v_pk_add_f32 v[58:59], v[58:59], 1.0 op_sel_hi:[1,0]
	s_nop 0
	v_pk_mul_f32 v[52:53], v[52:53], v[58:59]
	v_pk_add_f32 v[58:59], v[42:43], v[60:61] op_sel_hi:[0,1]
	v_pk_mul_f32 v[52:53], v[52:53], v[58:59]
	ds_read_b128 v[58:61], v169 offset:49152
	v_cvt_pk_bf16_f32 v55, v52, v53
	global_store_dwordx2 v[56:57], v[54:55], off offset:96
	ds_read_b128 v[52:55], v168 offset:49152
	s_waitcnt lgkmcnt(0)
	v_mfma_f32_16x16x32_bf16 v[52:55], v[52:55], v[0:3], 0
	v_mfma_f32_16x16x32_bf16 v[52:55], v[58:61], v[4:7], v[52:55]
	ds_read_b128 v[58:61], v170 offset:49152
	s_waitcnt lgkmcnt(0)
	v_mfma_f32_16x16x32_bf16 v[52:55], v[58:61], v[8:11], v[52:55]
	ds_read_b128 v[58:61], v171 offset:49152
	s_waitcnt lgkmcnt(0)
	v_mfma_f32_16x16x32_bf16 v[52:55], v[58:61], v[12:15], v[52:55]
	s_waitcnt vmcnt(7)
	v_lshlrev_b32_e32 v58, 16, v50
	v_and_b32_e32 v59, 0xffff0000, v50
	v_pk_mul_f32 v[60:61], v[58:59], s[20:21] op_sel_hi:[1,0]
	s_nop 3
	v_pk_add_f32 v[52:53], v[42:43], v[52:53] op_sel_hi:[0,1]
	v_pk_mul_f32 v[60:61], v[60:61], v[58:59]
	v_pk_add_f32 v[54:55], v[42:43], v[54:55] op_sel_hi:[0,1]
	v_pk_fma_f32 v[60:61], v[60:61], v[58:59], v[58:59]
	v_pk_mul_f32 v[58:59], v[58:59], 0.5 op_sel_hi:[1,0]
	v_pk_mul_f32 v[60:61], v[60:61], s[22:23] op_sel_hi:[1,0]
	s_nop 0
	v_mul_f32_e64 v50, |v60|, -2.0
	v_mul_f32_e32 v50, 0x3fb8aa3b, v50
	v_exp_f32_e32 v62, v50
	v_cmp_gt_f32_e32 vcc, 0, v60
	v_cmp_gt_f32_e64 s[4:5], 0, v61
	v_add_f32_e32 v50, 1.0, v62
	v_rcp_f32_e32 v104, v50
	v_mul_f32_e64 v50, |v61|, -2.0
	v_mul_f32_e32 v50, 0x3fb8aa3b, v50
	v_exp_f32_e32 v63, v50
	s_nop 0
	v_add_f32_e32 v50, 1.0, v63
	v_rcp_f32_e32 v105, v50
	v_pk_add_f32 v[106:107], v[62:63], 1.0 op_sel_hi:[1,0] neg_lo:[1,0] neg_hi:[1,0]
	v_lshlrev_b32_e32 v50, 16, v51
	v_and_b32_e32 v51, 0xffff0000, v51
	v_pk_mul_f32 v[62:63], v[106:107], v[104:105]
	s_nop 0
	v_cndmask_b32_e64 v61, v63, -v63, s[4:5]
	v_cndmask_b32_e64 v60, v62, -v62, vcc
	v_pk_add_f32 v[60:61], v[60:61], 1.0 op_sel_hi:[1,0]
	s_nop 0
	v_pk_mul_f32 v[58:59], v[58:59], v[60:61]
	s_nop 0
	v_pk_mul_f32 v[52:53], v[58:59], v[52:53]
	v_pk_mul_f32 v[58:59], v[50:51], s[20:21] op_sel_hi:[1,0]
	v_cvt_pk_bf16_f32 v52, v52, v53
	v_pk_mul_f32 v[58:59], v[58:59], v[50:51]
	s_nop 0
	v_pk_fma_f32 v[58:59], v[58:59], v[50:51], v[50:51]
	v_pk_mul_f32 v[50:51], v[50:51], 0.5 op_sel_hi:[1,0]
	v_pk_mul_f32 v[58:59], v[58:59], s[22:23] op_sel_hi:[1,0]
	s_nop 0
	v_mul_f32_e64 v60, |v58|, -2.0
	v_mul_f32_e32 v60, 0x3fb8aa3b, v60
	v_exp_f32_e32 v60, v60
	v_cmp_gt_f32_e32 vcc, 0, v58
	v_cmp_gt_f32_e64 s[4:5], 0, v59
	v_add_f32_e32 v61, 1.0, v60
	v_rcp_f32_e32 v62, v61
	v_mul_f32_e64 v61, |v59|, -2.0
	v_mul_f32_e32 v61, 0x3fb8aa3b, v61
	v_exp_f32_e32 v61, v61
	s_nop 0
	v_pk_add_f32 v[104:105], v[60:61], 1.0 op_sel_hi:[1,0] neg_lo:[1,0] neg_hi:[1,0]
	v_add_f32_e32 v60, 1.0, v61
	v_rcp_f32_e32 v63, v60
	s_nop 0
	v_pk_mul_f32 v[60:61], v[104:105], v[62:63]
	s_nop 0
	v_cndmask_b32_e64 v59, v61, -v61, s[4:5]
	v_cndmask_b32_e64 v58, v60, -v60, vcc
	v_pk_add_f32 v[58:59], v[58:59], 1.0 op_sel_hi:[1,0]
	s_nop 0
	v_pk_mul_f32 v[50:51], v[50:51], v[58:59]
	ds_read_b128 v[58:61], v173 offset:53248
	v_pk_mul_f32 v[50:51], v[50:51], v[54:55]
	s_waitcnt vmcnt(6)
	v_lshlrev_b32_e32 v54, 16, v48
	v_cvt_pk_bf16_f32 v53, v50, v51
	global_store_dwordx2 v[56:57], v[52:53], off offset:128
	ds_read_b128 v[50:53], v172 offset:53248
	s_waitcnt lgkmcnt(0)
	v_mfma_f32_16x16x32_bf16 v[50:53], v[50:53], v[0:3], 0
	v_and_b32_e32 v55, 0xffff0000, v48
	v_mfma_f32_16x16x32_bf16 v[50:53], v[58:61], v[4:7], v[50:53]
	ds_read_b128 v[58:61], v174 offset:53248
	s_waitcnt lgkmcnt(0)
	v_mfma_f32_16x16x32_bf16 v[50:53], v[58:61], v[8:11], v[50:53]
	ds_read_b128 v[58:61], v175 offset:53248
	s_waitcnt lgkmcnt(0)
	v_mfma_f32_16x16x32_bf16 v[50:53], v[58:61], v[12:15], v[50:53]
	v_mul_f32_e64 v58, v54, s20
	v_mul_f32_e64 v59, v55, s20
	s_nop 5
	v_pk_add_f32 v[50:51], v[42:43], v[50:51] op_sel_hi:[0,1]
	v_pk_mul_f32 v[58:59], v[58:59], v[54:55]
	v_pk_add_f32 v[52:53], v[42:43], v[52:53] op_sel_hi:[0,1]
	v_pk_fma_f32 v[58:59], v[58:59], v[54:55], v[54:55]
	v_pk_mul_f32 v[54:55], v[54:55], 0.5 op_sel_hi:[1,0]
	v_pk_mul_f32 v[58:59], v[58:59], s[22:23] op_sel_hi:[1,0]
	s_nop 0
	v_mul_f32_e64 v48, |v58|, -2.0
	v_mul_f32_e32 v48, 0x3fb8aa3b, v48
	v_exp_f32_e32 v60, v48
	v_cmp_gt_f32_e32 vcc, 0, v58
	v_cmp_gt_f32_e64 s[4:5], 0, v59
	v_add_f32_e32 v48, 1.0, v60
	v_rcp_f32_e32 v62, v48
	v_mul_f32_e64 v48, |v59|, -2.0
	v_mul_f32_e32 v48, 0x3fb8aa3b, v48
	v_exp_f32_e32 v61, v48
	s_nop 0
	v_add_f32_e32 v48, 1.0, v61
	v_rcp_f32_e32 v63, v48
	v_pk_add_f32 v[104:105], v[60:61], 1.0 op_sel_hi:[1,0] neg_lo:[1,0] neg_hi:[1,0]
	v_lshlrev_b32_e32 v48, 16, v49
	v_and_b32_e32 v49, 0xffff0000, v49
	v_pk_mul_f32 v[60:61], v[104:105], v[62:63]
	s_nop 0
	v_cndmask_b32_e64 v59, v61, -v61, s[4:5]
	v_cndmask_b32_e64 v58, v60, -v60, vcc
	v_pk_add_f32 v[58:59], v[58:59], 1.0 op_sel_hi:[1,0]
	s_nop 0
	v_pk_mul_f32 v[54:55], v[54:55], v[58:59]
	s_nop 0
	v_pk_mul_f32 v[50:51], v[54:55], v[50:51]
	v_pk_mul_f32 v[54:55], v[48:49], s[20:21] op_sel_hi:[1,0]
	v_cvt_pk_bf16_f32 v50, v50, v51
	v_pk_mul_f32 v[54:55], v[54:55], v[48:49]
	s_nop 0
	v_pk_fma_f32 v[54:55], v[54:55], v[48:49], v[48:49]
	v_pk_mul_f32 v[48:49], v[48:49], 0.5 op_sel_hi:[1,0]
	v_pk_mul_f32 v[54:55], v[54:55], s[22:23] op_sel_hi:[1,0]
	s_nop 0
	v_mul_f32_e64 v58, |v54|, -2.0
	v_mul_f32_e32 v58, 0x3fb8aa3b, v58
	v_exp_f32_e32 v58, v58
	v_cmp_gt_f32_e32 vcc, 0, v54
	v_cmp_gt_f32_e64 s[4:5], 0, v55
	v_add_f32_e32 v59, 1.0, v58
	v_rcp_f32_e32 v60, v59
	v_mul_f32_e64 v59, |v55|, -2.0
	v_mul_f32_e32 v59, 0x3fb8aa3b, v59
	v_exp_f32_e32 v59, v59
	s_nop 0
	v_pk_add_f32 v[62:63], v[58:59], 1.0 op_sel_hi:[1,0] neg_lo:[1,0] neg_hi:[1,0]
	v_add_f32_e32 v58, 1.0, v59
	v_rcp_f32_e32 v61, v58
	s_nop 0
	v_pk_mul_f32 v[58:59], v[62:63], v[60:61]
	s_nop 0
	v_cndmask_b32_e64 v55, v59, -v59, s[4:5]
	v_cndmask_b32_e64 v54, v58, -v58, vcc
	v_pk_add_f32 v[54:55], v[54:55], 1.0 op_sel_hi:[1,0]
	s_nop 0
	v_pk_mul_f32 v[48:49], v[48:49], v[54:55]
	s_nop 0
	v_pk_mul_f32 v[48:49], v[48:49], v[52:53]
	ds_read_b128 v[52:55], v177 offset:57344
	v_cvt_pk_bf16_f32 v51, v48, v49
	global_store_dwordx2 v[56:57], v[50:51], off offset:160
	ds_read_b128 v[48:51], v176 offset:57344
	s_waitcnt lgkmcnt(0)
	v_mfma_f32_16x16x32_bf16 v[48:51], v[48:51], v[0:3], 0
	v_mfma_f32_16x16x32_bf16 v[48:51], v[52:55], v[4:7], v[48:51]
	ds_read_b128 v[52:55], v178 offset:57344
	s_waitcnt lgkmcnt(0)
	v_mfma_f32_16x16x32_bf16 v[48:51], v[52:55], v[8:11], v[48:51]
	ds_read_b128 v[52:55], v179 offset:57344
	s_waitcnt lgkmcnt(0)
	v_mfma_f32_16x16x32_bf16 v[48:51], v[52:55], v[12:15], v[48:51]
	s_waitcnt vmcnt(7)
	v_lshlrev_b32_e32 v52, 16, v46
	v_and_b32_e32 v53, 0xffff0000, v46
	v_pk_mul_f32 v[54:55], v[52:53], s[20:21] op_sel_hi:[1,0]
	s_nop 3
	v_pk_add_f32 v[48:49], v[42:43], v[48:49] op_sel_hi:[0,1]
	v_pk_mul_f32 v[54:55], v[54:55], v[52:53]
	v_pk_add_f32 v[50:51], v[42:43], v[50:51] op_sel_hi:[0,1]
	v_pk_fma_f32 v[54:55], v[54:55], v[52:53], v[52:53]
	v_pk_mul_f32 v[52:53], v[52:53], 0.5 op_sel_hi:[1,0]
	v_pk_mul_f32 v[54:55], v[54:55], s[22:23] op_sel_hi:[1,0]
	s_nop 0
	v_mul_f32_e64 v46, |v54|, -2.0
	v_mul_f32_e32 v46, 0x3fb8aa3b, v46
	v_exp_f32_e32 v58, v46
	v_cmp_gt_f32_e32 vcc, 0, v54
	v_cmp_gt_f32_e64 s[4:5], 0, v55
	v_add_f32_e32 v46, 1.0, v58
	v_rcp_f32_e32 v60, v46
	v_mul_f32_e64 v46, |v55|, -2.0
	v_mul_f32_e32 v46, 0x3fb8aa3b, v46
	v_exp_f32_e32 v59, v46
	s_nop 0
	v_add_f32_e32 v46, 1.0, v59
	v_rcp_f32_e32 v61, v46
	v_pk_add_f32 v[62:63], v[58:59], 1.0 op_sel_hi:[1,0] neg_lo:[1,0] neg_hi:[1,0]
	v_lshlrev_b32_e32 v46, 16, v47
	v_and_b32_e32 v47, 0xffff0000, v47
	v_pk_mul_f32 v[58:59], v[62:63], v[60:61]
	s_nop 0
	v_cndmask_b32_e64 v55, v59, -v59, s[4:5]
	v_cndmask_b32_e64 v54, v58, -v58, vcc
	v_pk_add_f32 v[54:55], v[54:55], 1.0 op_sel_hi:[1,0]
	s_nop 0
	v_pk_mul_f32 v[52:53], v[52:53], v[54:55]
	s_nop 0
	v_pk_mul_f32 v[48:49], v[52:53], v[48:49]
	v_pk_mul_f32 v[52:53], v[46:47], s[20:21] op_sel_hi:[1,0]
	v_cvt_pk_bf16_f32 v48, v48, v49
	v_pk_mul_f32 v[52:53], v[52:53], v[46:47]
	s_nop 0
	v_pk_fma_f32 v[52:53], v[52:53], v[46:47], v[46:47]
	v_pk_mul_f32 v[46:47], v[46:47], 0.5 op_sel_hi:[1,0]
	v_pk_mul_f32 v[52:53], v[52:53], s[22:23] op_sel_hi:[1,0]
	s_nop 0
	v_mul_f32_e64 v54, |v52|, -2.0
	v_mul_f32_e32 v54, 0x3fb8aa3b, v54
	v_exp_f32_e32 v54, v54
	v_cmp_gt_f32_e32 vcc, 0, v52
	v_cmp_gt_f32_e64 s[4:5], 0, v53
	v_add_f32_e32 v55, 1.0, v54
	v_rcp_f32_e32 v58, v55
	v_mul_f32_e64 v55, |v53|, -2.0
	v_mul_f32_e32 v55, 0x3fb8aa3b, v55
	v_exp_f32_e32 v55, v55
	s_nop 0
	v_pk_add_f32 v[60:61], v[54:55], 1.0 op_sel_hi:[1,0] neg_lo:[1,0] neg_hi:[1,0]
	v_add_f32_e32 v54, 1.0, v55
	v_rcp_f32_e32 v59, v54
	s_nop 0
	v_pk_mul_f32 v[54:55], v[60:61], v[58:59]
	s_nop 0
	v_cndmask_b32_e64 v53, v55, -v55, s[4:5]
	v_cndmask_b32_e64 v52, v54, -v54, vcc
	v_pk_add_f32 v[52:53], v[52:53], 1.0 op_sel_hi:[1,0]
	s_nop 0
	v_pk_mul_f32 v[46:47], v[46:47], v[52:53]
	s_nop 0
	v_pk_mul_f32 v[46:47], v[46:47], v[50:51]
	s_nop 0
	v_cvt_pk_bf16_f32 v49, v46, v47
	global_store_dwordx2 v[56:57], v[48:49], off offset:192
	ds_read_b128 v[46:49], v180 offset:61440
	s_waitcnt lgkmcnt(0)
	v_mfma_f32_16x16x32_bf16 v[0:3], v[46:49], v[0:3], 0
	ds_read_b128 v[46:49], v181 offset:61440
	s_waitcnt lgkmcnt(0)
	v_mfma_f32_16x16x32_bf16 v[0:3], v[46:49], v[4:7], v[0:3]
	ds_read_b128 v[4:7], v182 offset:61440
	s_waitcnt lgkmcnt(0)
	v_mfma_f32_16x16x32_bf16 v[0:3], v[4:7], v[8:11], v[0:3]
	ds_read_b128 v[4:7], v183 offset:61440
	s_waitcnt lgkmcnt(0)
	v_mfma_f32_16x16x32_bf16 v[0:3], v[4:7], v[12:15], v[0:3]
	s_waitcnt vmcnt(7)
	v_lshlrev_b32_e32 v4, 16, v44
	v_and_b32_e32 v5, 0xffff0000, v44
	v_pk_mul_f32 v[6:7], v[4:5], s[20:21] op_sel_hi:[1,0]
	s_nop 3
	v_pk_add_f32 v[0:1], v[42:43], v[0:1] op_sel_hi:[0,1]
	v_pk_mul_f32 v[6:7], v[6:7], v[4:5]
	v_pk_add_f32 v[2:3], v[42:43], v[2:3] op_sel_hi:[0,1]
	v_pk_fma_f32 v[6:7], v[6:7], v[4:5], v[4:5]
	v_pk_mul_f32 v[4:5], v[4:5], 0.5 op_sel_hi:[1,0]
	v_pk_mul_f32 v[6:7], v[6:7], s[22:23] op_sel_hi:[1,0]
	s_nop 0
	v_mul_f32_e64 v8, |v6|, -2.0
	v_mul_f32_e32 v8, 0x3fb8aa3b, v8
	v_exp_f32_e32 v8, v8
	v_cmp_gt_f32_e32 vcc, 0, v6
	v_cmp_gt_f32_e64 s[4:5], 0, v7
	v_add_f32_e32 v9, 1.0, v8
	v_rcp_f32_e32 v10, v9
	v_mul_f32_e64 v9, |v7|, -2.0
	v_mul_f32_e32 v9, 0x3fb8aa3b, v9
	v_exp_f32_e32 v9, v9
	s_nop 0
	v_pk_add_f32 v[12:13], v[8:9], 1.0 op_sel_hi:[1,0] neg_lo:[1,0] neg_hi:[1,0]
	v_add_f32_e32 v8, 1.0, v9
	v_rcp_f32_e32 v11, v8
	s_nop 0
	v_pk_mul_f32 v[8:9], v[12:13], v[10:11]
	s_nop 0
	v_cndmask_b32_e64 v7, v9, -v9, s[4:5]
	v_cndmask_b32_e64 v6, v8, -v8, vcc
	v_pk_add_f32 v[6:7], v[6:7], 1.0 op_sel_hi:[1,0]
	s_nop 0
	v_pk_mul_f32 v[4:5], v[4:5], v[6:7]
	s_nop 0
	v_pk_mul_f32 v[0:1], v[4:5], v[0:1]
	v_lshlrev_b32_e32 v4, 16, v45
	v_and_b32_e32 v5, 0xffff0000, v45
	v_pk_mul_f32 v[6:7], v[4:5], s[20:21] op_sel_hi:[1,0]
	v_cvt_pk_bf16_f32 v0, v0, v1
	v_pk_mul_f32 v[6:7], v[6:7], v[4:5]
	s_nop 0
	v_pk_fma_f32 v[6:7], v[6:7], v[4:5], v[4:5]
	v_pk_mul_f32 v[4:5], v[4:5], 0.5 op_sel_hi:[1,0]
	v_pk_mul_f32 v[6:7], v[6:7], s[22:23] op_sel_hi:[1,0]
	s_nop 0
	v_mul_f32_e64 v8, |v6|, -2.0
	v_mul_f32_e32 v8, 0x3fb8aa3b, v8
	v_exp_f32_e32 v8, v8
	v_cmp_gt_f32_e32 vcc, 0, v6
	v_cmp_gt_f32_e64 s[4:5], 0, v7
	v_add_f32_e32 v9, 1.0, v8
	v_rcp_f32_e32 v10, v9
	v_mul_f32_e64 v9, |v7|, -2.0
	v_mul_f32_e32 v9, 0x3fb8aa3b, v9
	v_exp_f32_e32 v9, v9
	s_nop 0
	v_pk_add_f32 v[12:13], v[8:9], 1.0 op_sel_hi:[1,0] neg_lo:[1,0] neg_hi:[1,0]
	v_add_f32_e32 v8, 1.0, v9
	v_rcp_f32_e32 v11, v8
	s_nop 0
	v_pk_mul_f32 v[8:9], v[12:13], v[10:11]
	s_nop 0
	v_cndmask_b32_e64 v7, v9, -v9, s[4:5]
	v_cndmask_b32_e64 v6, v8, -v8, vcc
	v_pk_add_f32 v[6:7], v[6:7], 1.0 op_sel_hi:[1,0]
	s_nop 0
	v_pk_mul_f32 v[4:5], v[4:5], v[6:7]
	s_nop 0
	v_pk_mul_f32 v[2:3], v[4:5], v[2:3]
	s_nop 0
	v_cvt_pk_bf16_f32 v1, v2, v3
	global_store_dwordx2 v[56:57], v[0:1], off offset:224
	s_cbranch_scc1 .LBB0_360

.LBB0_550:
	s_or_b64 exec, exec, s[14:15]
	s_cmpk_lg_i32 s36, 0x100
	s_cbranch_scc1 .Lmodp_stride_g
	s_cmpk_lt_i32 s23, 0x80
	s_cbranch_scc1 .LBB0_568
	s_addk_i32 s23, 0x80
	s_addk_i32 s22, 0x80
	s_cmpk_gt_i32 s23, 0x17f
	s_cbranch_scc1 .LBB0_568
	s_branch .LBB0_551
	s_nop 0
	s_nop 0
	s_nop 0
	s_nop 0
	s_nop 0
	s_nop 0
	s_nop 0
.Lmodp_stride_g:
	s_add_i32 s23, s23, s36
	s_add_i32 s22, s22, s36
	s_cmpk_gt_i32 s23, 0x17f
	s_cbranch_scc1 .LBB0_568
